# opt4: + split vmcnt waits/global loads in NSA sel/window/swa loops, overlap q and K loads in mixer B/C unit prologues
# speedup vs baseline: 1.0364x; 1.0082x over previous
; template <class KB>
; __device__ __forceinline__ void sel_run(int nit, KB kbof, const half8 (&qf)[2][2], const unsigned char* kf, const unsigned char* vf, const int (&tqs)[2], int qq,
;                                         f32x4 (&o)[2][4], float (&m)[2], float (&l)[2], int g) {
;     if (nit <= 0) return;
;     u32x2 ka[8], va[8];
;     int eA = kbof(0);
;     int kbA = 64 * (eA & 255);
;     {
;         const unsigned char* kp = kf + (size_t)(kbA >> 5) * 2048; const unsigned char* vp = vf + (size_t)(kbA >> 5) * 2048;
; #pragma unroll
;         for (int i = 0; i < 8; ++i) { ka[i] = *(const u32x2*)(kp + i * 512); va[i] = *(const u32x2*)(vp + i * 512); }
;     }
;     for (int it = 0; it < nit; ++it) {
;         const int eN = kbof((it + 1 < nit) ? it + 1 : it);
;         const int kbN = 64 * (eN & 255);
;         const unsigned maskA = (unsigned)eA >> 8;
;         bool selq[2], need[2];
; #pragma unroll
;         for (int s_ = 0; s_ < 2; ++s_) { selq[s_] = ((maskA >> (4 * s_ + qq)) & 1u) != 0u; need[s_] = ((maskA >> (4 * s_)) & 15u) != 0u; }
;         half8 kh[8];
; #pragma unroll
;         for (int i = 0; i < 8; ++i) kh[i] = fp8x8_to_half8(ka[i]);
;         {
;             const unsigned char* kp = kf + (size_t)(kbN >> 5) * 2048;
; #pragma unroll
;             for (int i = 0; i < 8; ++i) ka[i] = *(const u32x2*)(kp + i * 512);
;         }
.LBB0_928:
	s_or_b64 exec, exec, s[2:3]
	s_bcnt1_i32_b64 s2, vcc
	s_waitcnt lgkmcnt(0)
	s_add_i32 s44, s44, s2
	s_cmp_eq_u32 s44, 0
	s_cbranch_scc1 .LBB0_944
	v_mov_b32_e32 v2, s92
	flat_load_dwordx4 v[34:37], v[118:119]
	flat_load_dwordx4 v[38:41], v[118:119] offset:64
	ds_read_b32 v2, v2 offset:17152
	s_lshl_b64 s[12:13], s[78:79], 20
	flat_load_dwordx4 v[42:45], v[120:121]
	flat_load_dwordx4 v[46:49], v[120:121] offset:64
	v_lshl_add_u64 v[118:119], v[134:135], 0, s[12:13]
	v_lshl_add_u64 v[120:121], v[136:137], 0, s[12:13]
	s_waitcnt lgkmcnt(0)
	v_readfirstlane_b32 s13, v2
	s_lshl_b32 s3, s13, 6
	s_and_b32 s12, s3, 0x3fc0
	s_lshl_b32 s84, s12, 6
	v_lshl_add_u64 v[2:3], v[120:121], 0, s[84:85]
	v_lshl_add_u64 v[4:5], v[118:119], 0, s[84:85]
	global_load_dwordx2 v[124:125], v[4:5], off offset:3584
	global_load_dwordx2 v[128:129], v[4:5], off offset:3072
	global_load_dwordx2 v[152:153], v[4:5], off offset:2560
	global_load_dwordx2 v[154:155], v[4:5], off offset:2048
	global_load_dwordx2 v[160:161], v[4:5], off offset:1536
	global_load_dwordx2 v[162:163], v[4:5], off offset:1024
	global_load_dwordx2 v[168:169], v[4:5], off offset:512
	global_load_dwordx2 v[182:183], v[4:5], off
	global_load_dwordx2 v[122:123], v[2:3], off offset:3584
	global_load_dwordx2 v[126:127], v[2:3], off offset:3072
	global_load_dwordx2 v[156:157], v[2:3], off offset:2560
	global_load_dwordx2 v[158:159], v[2:3], off offset:2048
	global_load_dwordx2 v[180:181], v[2:3], off offset:1536
	global_load_dwordx2 v[184:185], v[2:3], off offset:1024
	global_load_dwordx2 v[186:187], v[2:3], off offset:512
	global_load_dwordx2 v[188:189], v[2:3], off
	s_add_i32 s3, s10, s14
	v_mov_b32_e32 v4, v1
	v_mov_b32_e32 v5, v1
	s_add_i32 s45, s3, s2
	v_mov_b32_e32 v2, v1
	v_mov_b32_e32 v3, v1
	v_mov_b64_e32 v[8:9], v[4:5]
	v_mov_b64_e32 v[12:13], v[4:5]
	v_mov_b64_e32 v[16:17], v[4:5]
	v_mov_b64_e32 v[20:21], v[4:5]
	v_mov_b64_e32 v[24:25], v[4:5]
	v_mov_b64_e32 v[32:33], v[4:5]
	v_mov_b64_e32 v[28:29], v[4:5]
	s_add_i32 s45, s45, s11
	s_mov_b32 s46, 0
	v_mov_b32_e32 v151, 0xf149f2ca
	v_mov_b32_e32 v147, 0
	v_mov_b64_e32 v[6:7], v[2:3]
	v_mov_b64_e32 v[10:11], v[2:3]
	v_mov_b64_e32 v[14:15], v[2:3]
	v_mov_b64_e32 v[18:19], v[2:3]
	v_mov_b64_e32 v[22:23], v[2:3]
	v_mov_b64_e32 v[30:31], v[2:3]
	v_mov_b64_e32 v[26:27], v[2:3]
	v_mov_b32_e32 v149, 0
	v_mov_b32_e32 v225, 0xf149f2ca
.LBB0_930:
	s_mov_b32 s2, s46
	s_add_i32 s46, s46, 1
	s_cmp_lt_u32 s46, s44
	s_cselect_b32 s2, s46, s2
	s_lshl_b32 s2, s2, 2
	s_add_i32 s2, s92, s2
	v_mov_b32_e32 v82, s2
	ds_read_b32 v82, v82 offset:17152
	s_and_b32 s2, s13, 0xf00
	s_waitcnt vmcnt(8) lgkmcnt(0)
	v_cvt_scalef32_pk_f16_fp8 v83, v124, 1.0 op_sel:[1,0,0]
	v_cvt_scalef32_pk_f16_fp8 v84, v125, 1.0
	v_cvt_scalef32_pk_f16_fp8 v85, v125, 1.0 op_sel:[1,0,0]
	v_readfirstlane_b32 s47, v82
	s_lshl_b32 s3, s47, 6
	s_cmp_lg_u32 s2, 0
	s_cselect_b64 s[10:11], -1, 0
	s_and_b32 s48, s3, 0x3fc0
	s_lshl_b32 s84, s48, 6
	v_cvt_scalef32_pk_f16_fp8 v82, v124, 1.0
	v_lshl_add_u64 v[124:125], v[118:119], 0, s[84:85]
	v_cvt_scalef32_pk_f16_fp8 v86, v182, 1.0
	v_cvt_scalef32_pk_f16_fp8 v87, v182, 1.0 op_sel:[1,0,0]
	v_cvt_scalef32_pk_f16_fp8 v88, v183, 1.0
	v_cvt_scalef32_pk_f16_fp8 v89, v183, 1.0 op_sel:[1,0,0]
	v_cvt_scalef32_pk_f16_fp8 v110, v168, 1.0
	v_cvt_scalef32_pk_f16_fp8 v111, v168, 1.0 op_sel:[1,0,0]
	v_cvt_scalef32_pk_f16_fp8 v112, v169, 1.0
	v_cvt_scalef32_pk_f16_fp8 v113, v169, 1.0 op_sel:[1,0,0]
	v_cvt_scalef32_pk_f16_fp8 v106, v162, 1.0
	v_cvt_scalef32_pk_f16_fp8 v107, v162, 1.0 op_sel:[1,0,0]
	v_cvt_scalef32_pk_f16_fp8 v108, v163, 1.0
	v_cvt_scalef32_pk_f16_fp8 v109, v163, 1.0 op_sel:[1,0,0]
	v_cvt_scalef32_pk_f16_fp8 v102, v160, 1.0
	v_cvt_scalef32_pk_f16_fp8 v103, v160, 1.0 op_sel:[1,0,0]
	v_cvt_scalef32_pk_f16_fp8 v104, v161, 1.0
	v_cvt_scalef32_pk_f16_fp8 v105, v161, 1.0 op_sel:[1,0,0]
	v_cvt_scalef32_pk_f16_fp8 v98, v154, 1.0
	v_cvt_scalef32_pk_f16_fp8 v99, v154, 1.0 op_sel:[1,0,0]
	v_cvt_scalef32_pk_f16_fp8 v100, v155, 1.0
	v_cvt_scalef32_pk_f16_fp8 v101, v155, 1.0 op_sel:[1,0,0]
	v_cvt_scalef32_pk_f16_fp8 v94, v152, 1.0
	v_cvt_scalef32_pk_f16_fp8 v95, v152, 1.0 op_sel:[1,0,0]
	v_cvt_scalef32_pk_f16_fp8 v96, v153, 1.0
	v_cvt_scalef32_pk_f16_fp8 v97, v153, 1.0 op_sel:[1,0,0]
	v_cvt_scalef32_pk_f16_fp8 v90, v128, 1.0
	v_cvt_scalef32_pk_f16_fp8 v91, v128, 1.0 op_sel:[1,0,0]
	v_cvt_scalef32_pk_f16_fp8 v92, v129, 1.0
	v_cvt_scalef32_pk_f16_fp8 v93, v129, 1.0 op_sel:[1,0,0]
	global_load_dwordx2 v[182:183], v[124:125], off
	global_load_dwordx2 v[168:169], v[124:125], off offset:512
	global_load_dwordx2 v[162:163], v[124:125], off offset:1024
	global_load_dwordx2 v[160:161], v[124:125], off offset:1536
	global_load_dwordx2 v[154:155], v[124:125], off offset:2048
	global_load_dwordx2 v[152:153], v[124:125], off offset:2560
	global_load_dwordx2 v[128:129], v[124:125], off offset:3072
	s_nop 0
	global_load_dwordx2 v[124:125], v[124:125], off offset:3584
	s_cmp_eq_u32 s2, 0
	s_cbranch_scc1 .LBB0_932
	v_mfma_f32_16x16x32_f16 v[54:57], v[86:89], v[34:37], 0
	v_mfma_f32_16x16x32_f16 v[62:65], v[106:109], v[34:37], 0
	v_mfma_f32_16x16x32_f16 v[70:73], v[98:101], v[34:37], 0
	v_mfma_f32_16x16x32_f16 v[78:81], v[90:93], v[34:37], 0
	v_mfma_f32_16x16x32_f16 v[54:57], v[110:113], v[38:41], v[54:57]
	v_mfma_f32_16x16x32_f16 v[62:65], v[102:105], v[38:41], v[62:65]
	v_mfma_f32_16x16x32_f16 v[70:73], v[94:97], v[38:41], v[70:73]
	v_mfma_f32_16x16x32_f16 v[78:81], v[82:85], v[38:41], v[78:81]

; __device__ __forceinline__ float shx(float v, int m) { return __shfl_xor(v, m); }
; template <class KB>
; __device__ __forceinline__ void sel_run(int nit, KB kbof, const half8 (&qf)[2][2], const unsigned char* kf, const unsigned char* vf, const int (&tqs)[2], int qq,
;                                         f32x4 (&o)[2][4], float (&m)[2], float (&l)[2], int g) {
;     ...
;         half8 vh[8];
; #pragma unroll
;         for (int i = 0; i < 8; ++i) vh[i] = fp8x8_to_half8(va[i]);
;         {
;             const unsigned char* vp = vf + (size_t)(kbN >> 5) * 2048;
; #pragma unroll
;             for (int i = 0; i < 8; ++i) va[i] = *(const u32x2*)(vp + i * 512);
;         }
; #pragma unroll
;         for (int s_ = 0; s_ < 2; ++s_)
;             if (need[s_]) {
;                 float p[4][4]; float mx = -1e30f;
;                 const int klim = selq[s_] ? tqs[s_] - kbA - 4 * g : -1;
; #pragma unroll
;                 for (int t = 0; t < 4; ++t)
; #pragma unroll
;                     for (int r = 0; r < 4; ++r) { if (16 * t + r <= klim) mx = fmaxf(mx, s[s_][t][r]); }
;                 if (__ballot(mx > m[s_] + RESC_THR) != 0ull) {
;                     mx = fmaxf(mx, shx(mx, 16)); mx = fmaxf(mx, shx(mx, 32));
;                     const float mn = fmaxf(m[s_], mx); const float corr = __builtin_amdgcn_exp2f(m[s_] - mn); m[s_] = mn;
;                     l[s_] = l[s_] * corr;
; #pragma unroll
;                     for (int dt = 0; dt < 4; ++dt) o[s_][dt] = o[s_][dt] * corr;
;                 }
.LBB0_934:
	s_waitcnt vmcnt(8)
	v_cvt_scalef32_pk_f16_fp8 v90, v122, 1.0
	v_cvt_scalef32_pk_f16_fp8 v91, v122, 1.0 op_sel:[1,0,0]
	v_cvt_scalef32_pk_f16_fp8 v92, v123, 1.0
	v_cvt_scalef32_pk_f16_fp8 v93, v123, 1.0 op_sel:[1,0,0]
	v_lshl_add_u64 v[122:123], v[120:121], 0, s[84:85]
	v_cvt_scalef32_pk_f16_fp8 v102, v188, 1.0
	v_cvt_scalef32_pk_f16_fp8 v103, v188, 1.0 op_sel:[1,0,0]
	v_cvt_scalef32_pk_f16_fp8 v104, v189, 1.0
	v_cvt_scalef32_pk_f16_fp8 v105, v189, 1.0 op_sel:[1,0,0]
	v_cvt_scalef32_pk_f16_fp8 v94, v186, 1.0
	v_cvt_scalef32_pk_f16_fp8 v95, v186, 1.0 op_sel:[1,0,0]
	v_cvt_scalef32_pk_f16_fp8 v96, v187, 1.0
	v_cvt_scalef32_pk_f16_fp8 v97, v187, 1.0 op_sel:[1,0,0]
	v_cvt_scalef32_pk_f16_fp8 v86, v184, 1.0
	v_cvt_scalef32_pk_f16_fp8 v87, v184, 1.0 op_sel:[1,0,0]
	v_cvt_scalef32_pk_f16_fp8 v88, v185, 1.0
	v_cvt_scalef32_pk_f16_fp8 v89, v185, 1.0 op_sel:[1,0,0]
	v_cvt_scalef32_pk_f16_fp8 v82, v180, 1.0
	v_cvt_scalef32_pk_f16_fp8 v83, v180, 1.0 op_sel:[1,0,0]
	v_cvt_scalef32_pk_f16_fp8 v84, v181, 1.0
	v_cvt_scalef32_pk_f16_fp8 v85, v181, 1.0 op_sel:[1,0,0]
	v_cvt_scalef32_pk_f16_fp8 v110, v158, 1.0
	v_cvt_scalef32_pk_f16_fp8 v111, v158, 1.0 op_sel:[1,0,0]
	v_cvt_scalef32_pk_f16_fp8 v112, v159, 1.0
	v_cvt_scalef32_pk_f16_fp8 v113, v159, 1.0 op_sel:[1,0,0]
	v_cvt_scalef32_pk_f16_fp8 v106, v156, 1.0
	v_cvt_scalef32_pk_f16_fp8 v107, v156, 1.0 op_sel:[1,0,0]
	v_cvt_scalef32_pk_f16_fp8 v108, v157, 1.0
	v_cvt_scalef32_pk_f16_fp8 v109, v157, 1.0 op_sel:[1,0,0]
	v_cvt_scalef32_pk_f16_fp8 v98, v126, 1.0
	v_cvt_scalef32_pk_f16_fp8 v99, v126, 1.0 op_sel:[1,0,0]
	v_cvt_scalef32_pk_f16_fp8 v100, v127, 1.0
	v_cvt_scalef32_pk_f16_fp8 v101, v127, 1.0 op_sel:[1,0,0]
	global_load_dwordx2 v[188:189], v[122:123], off
	global_load_dwordx2 v[186:187], v[122:123], off offset:512
	global_load_dwordx2 v[184:185], v[122:123], off offset:1024
	global_load_dwordx2 v[180:181], v[122:123], off offset:1536
	global_load_dwordx2 v[158:159], v[122:123], off offset:2048
	global_load_dwordx2 v[156:157], v[122:123], off offset:2560
	global_load_dwordx2 v[126:127], v[122:123], off offset:3072
	s_nop 0
	global_load_dwordx2 v[122:123], v[122:123], off offset:3584
	s_add_i32 s100, s12, 64
	s_lshr_b32 s33, s13, 8
	s_andn2_b64 vcc, exec, s[10:11]
	v_subrev_u32_e32 v226, s12, v213
	s_cbranch_vccnz .LBB0_938
	s_cmp_le_u32 s100, s93
	s_cbranch_scc1 .Lsel_fast0
	v_lshrrev_b32_e64 v227, v192, s33
	v_and_b32_e32 v227, 1, v227
	v_add_u32_e32 v228, v226, v223
	v_cmp_eq_u32_e32 vcc, 1, v227
	v_max_f32_e32 v229, v55, v55
	v_max_f32_e32 v230, v63, v63
	v_cndmask_b32_e32 v227, -1, v228, vcc
	v_max_f32_e32 v228, v54, v54
	v_max_f32_e32 v228, 0xf149f2ca, v228
	v_cmp_gt_i32_e64 s[42:43], 0, v227
	v_cmp_gt_i32_e64 s[40:41], 1, v227
	v_cmp_gt_i32_e64 s[38:39], 2, v227
	v_cndmask_b32_e64 v228, v228, v172, s[42:43]
	v_max_f32_e32 v229, v228, v229
	v_cndmask_b32_e64 v228, v229, v228, s[40:41]
	v_max_f32_e32 v229, v56, v56
	v_max_f32_e32 v229, v228, v229
	v_cndmask_b32_e64 v228, v229, v228, s[38:39]
	v_max_f32_e32 v229, v57, v57
	v_max_f32_e32 v229, v228, v229
	v_cmp_gt_i32_e64 s[36:37], 3, v227
	v_cmp_gt_i32_e64 s[34:35], 16, v227
	v_cmp_gt_i32_e64 s[30:31], 17, v227
	v_cndmask_b32_e64 v228, v229, v228, s[36:37]
	v_max_f32_e32 v229, v62, v62
	v_max_f32_e32 v229, v228, v229
	v_cndmask_b32_e64 v228, v229, v228, s[34:35]
	v_max_f32_e32 v229, v228, v228
	v_max_f32_e32 v229, v229, v230
	v_cndmask_b32_e64 v228, v229, v228, s[30:31]
	v_max_f32_e32 v229, v228, v228
	v_max_f32_e32 v230, v64, v64
	v_max_f32_e32 v229, v229, v230
	v_cmp_gt_i32_e64 s[28:29], 18, v227
	v_max_f32_e32 v230, v65, v65
	v_cmp_gt_i32_e64 s[26:27], 19, v227
	v_cndmask_b32_e64 v228, v229, v228, s[28:29]
	v_max_f32_e32 v229, v228, v228
	v_max_f32_e32 v229, v229, v230
	v_cndmask_b32_e64 v228, v229, v228, s[26:27]
	v_max_f32_e32 v229, v228, v228
	v_max_f32_e32 v230, v70, v70
	v_max_f32_e32 v229, v229, v230
	v_cmp_gt_i32_e64 s[24:25], 32, v227
	v_max_f32_e32 v230, v71, v71
	v_cmp_gt_i32_e64 s[22:23], 33, v227
	v_cndmask_b32_e64 v228, v229, v228, s[24:25]
	v_max_f32_e32 v229, v228, v228
	v_max_f32_e32 v229, v229, v230
	v_cndmask_b32_e64 v228, v229, v228, s[22:23]
	v_max_f32_e32 v229, v228, v228
	v_max_f32_e32 v230, v72, v72
	v_max_f32_e32 v229, v229, v230
	v_cmp_gt_i32_e64 s[20:21], 34, v227
	v_max_f32_e32 v230, v73, v73
	v_cmp_gt_i32_e64 s[18:19], 35, v227
	v_cndmask_b32_e64 v228, v229, v228, s[20:21]
	v_max_f32_e32 v229, v228, v228
	v_max_f32_e32 v229, v229, v230
	v_cndmask_b32_e64 v228, v229, v228, s[18:19]
	v_max_f32_e32 v229, v228, v228
	v_max_f32_e32 v230, v78, v78
	v_max_f32_e32 v229, v229, v230
	v_cmp_gt_i32_e64 s[16:17], 48, v227
	v_max_f32_e32 v230, v79, v79
	v_cmp_gt_i32_e64 s[14:15], 49, v227
	v_cndmask_b32_e64 v228, v229, v228, s[16:17]
	v_max_f32_e32 v229, v228, v228
	v_max_f32_e32 v229, v229, v230
	v_cndmask_b32_e64 v228, v229, v228, s[14:15]
	v_max_f32_e32 v229, v228, v228
	v_max_f32_e32 v230, v80, v80
	v_max_f32_e32 v229, v229, v230
	v_cmp_gt_i32_e64 s[12:13], 50, v227
	v_max_f32_e32 v230, v81, v81
	v_cmp_gt_i32_e64 s[10:11], 51, v227
	v_cndmask_b32_e64 v228, v229, v228, s[12:13]
	v_max_f32_e32 v229, v228, v228
	v_max_f32_e32 v229, v229, v230
	v_cndmask_b32_e64 v227, v229, v228, s[10:11]
	v_add_f32_e32 v228, 0x41400000, v225
	v_cmp_gt_f32_e32 vcc, v227, v228
	s_cbranch_vccz .LBB0_937
	ds_bpermute_b32 v228, v173, v227
	v_max_f32_e32 v227, v227, v227
	s_waitcnt lgkmcnt(0)
	v_max_f32_e32 v228, v228, v228
	v_max_f32_e32 v227, v227, v228
	ds_bpermute_b32 v228, v222, v227
	s_waitcnt lgkmcnt(0)
	v_max3_f32 v227, v225, v227, v228
	v_sub_f32_e32 v225, v225, v227
	v_exp_f32_e32 v228, v225
	v_mov_b32_e32 v225, v227
	v_mul_f32_e32 v149, v149, v228
	v_pk_mul_f32 v[28:29], v[28:29], v[228:229] op_sel_hi:[1,0]
	v_pk_mul_f32 v[26:27], v[26:27], v[228:229] op_sel_hi:[1,0]
	v_pk_mul_f32 v[32:33], v[32:33], v[228:229] op_sel_hi:[1,0]
	v_pk_mul_f32 v[30:31], v[30:31], v[228:229] op_sel_hi:[1,0]
	v_pk_mul_f32 v[24:25], v[24:25], v[228:229] op_sel_hi:[1,0]
	v_pk_mul_f32 v[22:23], v[22:23], v[228:229] op_sel_hi:[1,0]
	v_pk_mul_f32 v[20:21], v[20:21], v[228:229] op_sel_hi:[1,0]
	v_pk_mul_f32 v[18:19], v[18:19], v[228:229] op_sel_hi:[1,0]

; #define LDS_WAIT() asm volatile("s_waitcnt lgkmcnt(0)" ::: "memory")
; __device__ __forceinline__ float shx(float v, int m) { return __shfl_xor(v, m); }
; __device__ __forceinline__ void a_unit(const ACtx& X, int b, int t0, float* ldsw, int lane) {
;     ...
; #pragma unroll
;         for (int s_ = 0; s_ < 2; ++s_) {
;             float ls = l[s_]; ls += shx(ls, 16); ls += shx(ls, 32);
;             const float gs = (float)P[(rowb + tqs[s_]) * NPROJ + 38 * 64 + h * 3 + 1] / fmaxf(ls, 1e-30f);
; #pragma unroll
;             for (int dt = 0; dt < 4; ++dt)
; #pragma unroll
;                 for (int r = 0; r < 4; ++r) outT[((4 * s_ + qq) * 4 + h) * OTS + 16 * dt + 4 * g + r] += gs * o[s_][dt][r];
;         }
;         LDS_WAIT(); __builtin_amdgcn_wave_barrier();
;     }
;     {
;         const int q8 = c & 7, tq = t0 + q8;
;         half8 qf[2][2];
; #pragma unroll
;         for (int s_ = 0; s_ < 2; ++s_) { const half_t* qrow = P + (rowb + tq) * NPROJ + (2 * s_ + (c >> 3)) * 64; qf[s_][0] = *(const half8*)(qrow + 8 * g); qf[s_][1] = *(const half8*)(qrow + 32 + 8 * g); }
;         const half_t* kb_ = X.kf + (size_t)(1 * 2 + b) * 64 * S + loff;
;         const half_t* vb_ = X.vt + (size_t)(1 * 2 + b) * 64 * S + loff;
;         auto valid = [&](int, int key) { return key <= tq && tq - key <= 511; };
;         float m[2] = {-1e30f, -1e30f}, l[2] = {0.f, 0.f}; f32x4 o[2][4];
; #pragma unroll
;         for (int s_ = 0; s_ < 2; ++s_)
; #pragma unroll
;             for (int dt = 0; dt < 4; ++dt) o[s_][dt] = (f32x4){0.f, 0.f, 0.f, 0.f};
;         const int lo_ = t0 - 511; const int kb0 = (lo_ > 0 ? lo_ : 0) & ~31;
;         auto kbw = [&](int it) { return kb0 + 64 * it; };
;         attn_runN<2, 0>(((((t0 + 7) >> 5) - (kb0 >> 5)) >> 1) + 1, kbw, S / 32 - 1, qf, kb_, vb_, valid, o, m, l, g);
.LBB0_945:
	ds_bpermute_b32 v34, v173, v149
	s_max_i32 s47, s93, 0x1ff
	s_addk_i32 s47, 0xfe01
	v_mov_b32_e32 v151, 0
	s_waitcnt lgkmcnt(0)
	v_add_f32_e32 v34, v149, v34
	ds_bpermute_b32 v35, v222, v34
	v_or_b32_e32 v149, s93, v215
	s_waitcnt lgkmcnt(0)
	v_add_f32_e32 v36, v34, v35
	v_lshl_add_u64 v[34:35], v[138:139], 0, v[116:117]
	v_add_co_u32_e32 v34, vcc, 0x1000, v34
	s_nop 1
	v_addc_co_u32_e32 v35, vcc, 0, v35, vcc
	flat_load_ushort v34, v[34:35] offset:770
	v_max_f32_e32 v35, 0xda24260, v36
	s_waitcnt vmcnt(0) lgkmcnt(0)
	v_cvt_f32_f16_e32 v34, v34
	v_div_scale_f32 v36, s[2:3], v35, v35, v34
	v_rcp_f32_e32 v37, v36
	s_movk_i32 s2, 0x1000
	v_fma_f32 v38, -v36, v37, 1.0
	v_fmac_f32_e32 v37, v38, v37
	v_div_scale_f32 v38, vcc, v34, v35, v34
	v_mul_f32_e32 v39, v38, v37
	v_fma_f32 v40, -v36, v39, v38
	v_fmac_f32_e32 v39, v40, v37
	v_fma_f32 v36, -v36, v39, v38
	v_div_fmas_f32 v36, v36, v37, v39
	v_div_fixup_f32 v38, v36, v35, v34
	ds_read_b128 v[34:37], v216
	s_waitcnt lgkmcnt(0)
	v_pk_fma_f32 v[26:27], v[26:27], v[38:39], v[34:35] op_sel_hi:[1,0,1]
	v_pk_fma_f32 v[28:29], v[28:29], v[38:39], v[36:37] op_sel_hi:[1,0,1]
	ds_write_b128 v216, v[26:29]
	ds_read_b128 v[26:29], v216 offset:64
	s_waitcnt lgkmcnt(0)
	v_pk_fma_f32 v[26:27], v[30:31], v[38:39], v[26:27] op_sel_hi:[1,0,1]
	v_pk_fma_f32 v[28:29], v[32:33], v[38:39], v[28:29] op_sel_hi:[1,0,1]
	ds_write_b128 v216, v[26:29] offset:64
	ds_read_b128 v[26:29], v216 offset:128
	v_mov_b32_e32 v33, 0
	v_mov_b32_e32 v32, 0
	v_mov_b32_e32 v31, 0
	v_mov_b32_e32 v30, 0
	s_waitcnt lgkmcnt(0)
	v_pk_fma_f32 v[22:23], v[22:23], v[38:39], v[26:27] op_sel_hi:[1,0,1]
	v_pk_fma_f32 v[24:25], v[24:25], v[38:39], v[28:29] op_sel_hi:[1,0,1]
	ds_write_b128 v216, v[22:25] offset:128
	ds_read_b128 v[22:25], v216 offset:192
	v_mov_b32_e32 v29, 0
	v_mov_b32_e32 v28, 0
	v_mov_b32_e32 v27, 0
	v_mov_b32_e32 v26, 0
	s_waitcnt lgkmcnt(0)
	v_pk_fma_f32 v[18:19], v[18:19], v[38:39], v[22:23] op_sel_hi:[1,0,1]
	v_pk_fma_f32 v[20:21], v[20:21], v[38:39], v[24:25] op_sel_hi:[1,0,1]
	ds_write_b128 v216, v[18:21] offset:192
	ds_bpermute_b32 v18, v173, v147
	v_mov_b32_e32 v25, 0
	s_waitcnt lgkmcnt(0)
	v_add_f32_e32 v18, v147, v18
	ds_bpermute_b32 v19, v222, v18
	v_mov_b32_e32 v147, 0
	s_waitcnt lgkmcnt(0)
	v_add_f32_e32 v20, v18, v19
	v_lshl_add_u64 v[18:19], v[138:139], 0, v[114:115]
	v_add_co_u32_e32 v18, vcc, s2, v18
	s_nop 1
	v_addc_co_u32_e32 v19, vcc, 0, v19, vcc
	flat_load_ushort v18, v[18:19] offset:770
	v_max_f32_e32 v19, 0xda24260, v20
	s_waitcnt vmcnt(0) lgkmcnt(0)
	v_cvt_f32_f16_e32 v18, v18
	v_div_scale_f32 v20, s[2:3], v19, v19, v18
	v_rcp_f32_e32 v21, v20
	v_readlane_b32 s2, v253, 39
	v_readlane_b32 s3, v253, 40
	v_fma_f32 v22, -v20, v21, 1.0
	v_fmac_f32_e32 v21, v22, v21
	v_div_scale_f32 v22, vcc, v18, v19, v18
	v_mul_f32_e32 v23, v22, v21
	v_fma_f32 v24, -v20, v23, v22
	v_fmac_f32_e32 v23, v24, v21
	v_fma_f32 v20, -v20, v23, v22
	v_div_fmas_f32 v20, v20, v21, v23
	v_div_fixup_f32 v22, v20, v19, v18
	ds_read_b128 v[18:21], v216 offset:4352
	v_mov_b32_e32 v24, 0
	s_waitcnt lgkmcnt(0)
	v_pk_fma_f32 v[14:15], v[14:15], v[22:23], v[18:19] op_sel_hi:[1,0,1]
	v_pk_fma_f32 v[16:17], v[16:17], v[22:23], v[20:21] op_sel_hi:[1,0,1]
	ds_write_b128 v216, v[14:17] offset:4352
	ds_read_b128 v[14:17], v216 offset:4416
	v_mov_b32_e32 v21, 0
	v_mov_b32_e32 v20, 0
	v_mov_b32_e32 v19, 0
	v_mov_b32_e32 v18, 0
	s_waitcnt lgkmcnt(0)
	v_pk_fma_f32 v[10:11], v[10:11], v[22:23], v[14:15] op_sel_hi:[1,0,1]
	v_pk_fma_f32 v[12:13], v[12:13], v[22:23], v[16:17] op_sel_hi:[1,0,1]
	ds_write_b128 v216, v[10:13] offset:4416
	ds_read_b128 v[10:13], v216 offset:4480
	v_mov_b32_e32 v17, 0
	v_mov_b32_e32 v16, 0
	v_mov_b32_e32 v15, 0
	v_mov_b32_e32 v14, 0
	s_waitcnt lgkmcnt(0)
	v_pk_fma_f32 v[6:7], v[6:7], v[22:23], v[10:11] op_sel_hi:[1,0,1]
	v_pk_fma_f32 v[8:9], v[8:9], v[22:23], v[12:13] op_sel_hi:[1,0,1]
	ds_write_b128 v216, v[6:9] offset:4480
	ds_read_b128 v[6:9], v216 offset:4544
	v_mov_b32_e32 v13, 0
	v_mov_b32_e32 v12, 0
	v_mov_b32_e32 v11, 0
	v_mov_b32_e32 v10, 0
	s_waitcnt lgkmcnt(0)
	v_pk_fma_f32 v[2:3], v[2:3], v[22:23], v[6:7] op_sel_hi:[1,0,1]
	v_pk_fma_f32 v[4:5], v[4:5], v[22:23], v[8:9] op_sel_hi:[1,0,1]
	ds_write_b128 v216, v[2:5] offset:4544
	v_or_b32_e32 v4, s96, v149
	v_mov_b64_e32 v[2:3], s[2:3]
	v_mad_u64_u32 v[152:153], s[2:3], v4, s82, v[2:3]
	s_lshr_b32 s3, s93, 5
	s_lshr_b32 s2, s47, 5
	s_waitcnt lgkmcnt(0)
	s_sub_i32 s3, s3, s2
	s_ashr_i32 s46, s3, 1
	v_mad_u32_u24 v153, s97, v203, v153
	s_cmp_lt_i32 s46, 0
	v_mov_b32_e32 v23, 0
	v_mov_b32_e32 v22, 0
	v_mov_b32_e32 v9, 0
	v_mov_b32_e32 v8, 0
	v_mov_b32_e32 v7, 0
	v_mov_b32_e32 v6, 0
	v_mov_b32_e32 v5, 0
	v_mov_b32_e32 v4, 0
	v_mov_b32_e32 v3, 0
	v_mov_b32_e32 v2, 0
	s_cbranch_scc1 .LBB0_687
	s_lshl_b32 s3, s78, 21
	v_mov_b32_e32 v147, v1
	s_or_b32 s84, s3, 0x400000
	s_min_u32 s3, s2, 0x1fe
	v_lshl_add_u64 v[2:3], v[152:153], 0, v[146:147]
	v_lshlrev_b32_e32 v4, 1, v164
	v_mov_b32_e32 v5, v1
	s_lshl_b32 s3, s3, 12
	v_lshl_add_u64 v[2:3], v[2:3], 0, v[4:5]
	v_lshl_add_u64 v[154:155], v[140:141], 0, s[84:85]
	v_lshl_add_u64 v[156:157], v[142:143], 0, s[84:85]
	s_add_i32 s84, s3, 0x1000
	s_mov_b32 s3, s85
	global_load_dwordx4 v[34:37], v[2:3], off
	global_load_dwordx4 v[38:41], v[2:3], off offset:64
	global_load_dwordx4 v[42:45], v[2:3], off offset:256
	global_load_dwordx4 v[46:49], v[2:3], off offset:320
	s_lshl_b64 s[2:3], s[2:3], 12
	v_lshl_add_u64 v[2:3], v[154:155], 0, s[84:85]
	v_lshl_add_u64 v[4:5], v[154:155], 0, s[2:3]
	global_load_dwordx4 v[50:53], v[2:3], off offset:3072
	global_load_dwordx4 v[54:57], v[2:3], off offset:2048
	global_load_dwordx4 v[66:69], v[4:5], off offset:3072
	global_load_dwordx4 v[74:77], v[4:5], off offset:2048
	global_load_dwordx4 v[58:61], v[2:3], off offset:1024
	global_load_dwordx4 v[62:65], v[2:3], off
	global_load_dwordx4 v[78:81], v[4:5], off offset:1024
	global_load_dwordx4 v[70:73], v[4:5], off
	v_mov_b32_e32 v4, v1
	v_mov_b32_e32 v5, v1
	s_andn2_b32 s47, s47, 31
	v_mov_b32_e32 v2, v1
	v_mov_b32_e32 v3, v1
	v_mov_b64_e32 v[8:9], v[4:5]
	v_mov_b64_e32 v[12:13], v[4:5]
	v_mov_b64_e32 v[16:17], v[4:5]
	v_mov_b64_e32 v[20:21], v[4:5]
	v_mov_b64_e32 v[24:25], v[4:5]
	v_mov_b64_e32 v[28:29], v[4:5]
	v_mov_b64_e32 v[32:33], v[4:5]
	v_lshl_add_u64 v[86:87], v[156:157], 0, s[84:85]
	v_lshl_add_u64 v[82:83], v[156:157], 0, s[2:3]
	v_add_u32_e32 v162, 0xfffffe00, v149
	s_mov_b32 s48, 0
	v_mov_b32_e32 v163, 0xf149f2ca
	v_mov_b32_e32 v147, 0
	v_mov_b64_e32 v[6:7], v[2:3]
	v_mov_b64_e32 v[10:11], v[2:3]
	v_mov_b64_e32 v[14:15], v[2:3]
	v_mov_b64_e32 v[18:19], v[2:3]
	v_mov_b64_e32 v[22:23], v[2:3]
	v_mov_b64_e32 v[26:27], v[2:3]
	v_mov_b64_e32 v[30:31], v[2:3]
	v_mov_b32_e32 v151, 0
	v_mov_b32_e32 v168, 0xf149f2ca
	s_mov_b32 s49, s47
; #define MFMA16(a, b, c) __builtin_amdgcn_mfma_f32_16x16x32_f16((a), (b), (c), 0, 0, 0)
; __device__ __forceinline__ float shx(float v, int m) { return __shfl_xor(v, m); }
;     ...
;     for (int it = 0; it < nit; ++it) {
;         const int kbN = kbof((it + 1 < nit) ? it + 1 : it);
;         const int nbA = kbN >> 5, nbB = (nbA + 1 <= maxblk) ? nbA + 1 : maxblk;
;         const f32x4 z = {0.f, 0.f, 0.f, 0.f};
; #pragma unroll
;         for (int s_ = 0; s_ < NS; ++s_) {
;             f32x4 s[4];
; #pragma unroll
;             for (int t = 0; t < 4; ++t) { s[t] = MFMA16(ka[2 * t], qf[s_][0], z); s[t] = MFMA16(ka[2 * t + 1], qf[s_][1], s[t]); }
;             if (s_ == NS - 1) {
;                 const half_t* kpA = kf + (size_t)nbA * 2048; const half_t* kpB = kf + (size_t)nbB * 2048;
; #pragma unroll
;                 for (int i = 0; i < 4; ++i) { ka[i] = *(const half8*)(kpA + i * 512); ka[4 + i] = *(const half8*)(kpB + i * 512); }
;             }
;             if (MODE != 1) {
;                 float mx = -1e30f;
; #pragma unroll
;                 for (int t = 0; t < 4; ++t)
; #pragma unroll
;                     for (int r = 0; r < 4; ++r) { if (valid(s_, kbA + 16 * t + 4 * g + r)) mx = fmaxf(mx, s[t][r]); }
;                 if (__ballot(mx > m[s_] + RESC_THR) != 0ull) {
;                     mx = fmaxf(mx, shx(mx, 16)); mx = fmaxf(mx, shx(mx, 32));
;                     const float mn = fmaxf(m[s_], mx); const float corr = __builtin_amdgcn_exp2f(m[s_] - mn); m[s_] = mn; l[s_] = l[s_] * corr;
;                     if (PV) {
; #pragma unroll
;                         for (int dt = 0; dt < 4; ++dt) o[s_][dt] = o[s_][dt] * corr;
;                     }
;                 }
;             }
.LBB0_947:
	global_load_dwordx4 v[106:109], v[82:83], off
	global_load_dwordx4 v[98:101], v[82:83], off offset:1024
	global_load_dwordx4 v[90:93], v[82:83], off offset:2048
	s_nop 0
	global_load_dwordx4 v[82:85], v[82:83], off offset:3072
	s_nop 0
	global_load_dwordx4 v[110:113], v[86:87], off
	global_load_dwordx4 v[102:105], v[86:87], off offset:1024
	global_load_dwordx4 v[94:97], v[86:87], off offset:2048
	s_nop 0
	global_load_dwordx4 v[86:89], v[86:87], off offset:3072
	s_waitcnt vmcnt(8) lgkmcnt(0)
	v_mfma_f32_16x16x32_f16 v[114:117], v[70:73], v[34:37], 0
	v_add_u32_e32 v158, s49, v166
	v_cmp_le_i32_e32 vcc, v158, v149
	v_cmp_gt_i32_e64 s[10:11], v158, v162
	v_mfma_f32_16x16x32_f16 v[126:129], v[78:81], v[38:41], v[114:117]
	s_and_b64 s[10:11], vcc, s[10:11]
	v_sub_u32_e32 v160, v158, v149
	s_movk_i32 s2, 0xfdff
	v_cmp_lt_i32_e32 vcc, v158, v149
	v_cmp_lt_i32_e64 s[12:13], s2, v160
	s_nop 2
	v_max_f32_e32 v159, v126, v126
	v_max_f32_e32 v159, 0xf149f2ca, v159
	v_cndmask_b32_e64 v159, v172, v159, s[10:11]
	v_max_f32_e32 v160, v127, v127
	v_mfma_f32_16x16x32_f16 v[114:117], v[74:77], v[34:37], 0
	s_and_b64 s[12:13], vcc, s[12:13]
	v_max_f32_e32 v160, v159, v160
	v_cndmask_b32_e64 v159, v159, v160, s[12:13]
	v_add_u32_e32 v160, 2, v158
	v_cmp_le_i32_e32 vcc, v160, v149
	v_cmp_gt_i32_e64 s[14:15], v160, v162
	v_max_f32_e32 v160, v128, v128
	s_and_b64 s[14:15], vcc, s[14:15]
	v_max_f32_e32 v160, v159, v160
	v_mfma_f32_16x16x32_f16 v[122:125], v[66:69], v[38:41], v[114:117]
	v_cndmask_b32_e64 v159, v159, v160, s[14:15]
	v_add_u32_e32 v160, 3, v158
	v_cmp_le_i32_e32 vcc, v160, v149
	v_cmp_gt_i32_e64 s[16:17], v160, v162
	v_max_f32_e32 v160, v129, v129
	s_and_b64 s[18:19], vcc, s[16:17]
	v_max_f32_e32 v160, v159, v160
	v_cndmask_b32_e64 v159, v159, v160, s[18:19]
	v_add_u32_e32 v160, 16, v158
	v_cmp_le_i32_e32 vcc, v160, v149
	v_cmp_gt_i32_e64 s[16:17], v160, v162
	v_max_f32_e32 v160, v122, v122
	s_and_b64 s[16:17], vcc, s[16:17]
	v_max_f32_e32 v160, v159, v160
	v_cndmask_b32_e64 v159, v159, v160, s[16:17]
	v_add_u32_e32 v160, 17, v158
	v_cmp_le_i32_e32 vcc, v160, v149
	v_cmp_gt_i32_e64 s[20:21], v160, v162
	v_max_f32_e32 v160, v159, v159
	v_max_f32_e32 v161, v123, v123
	v_mfma_f32_16x16x32_f16 v[114:117], v[62:65], v[34:37], 0
	s_and_b64 s[20:21], vcc, s[20:21]
	v_max_f32_e32 v160, v160, v161
	v_cndmask_b32_e64 v159, v159, v160, s[20:21]
	v_add_u32_e32 v160, 18, v158
	v_cmp_le_i32_e32 vcc, v160, v149
	v_cmp_gt_i32_e64 s[22:23], v160, v162
	v_max_f32_e32 v160, v159, v159
	v_max_f32_e32 v161, v124, v124
	s_and_b64 s[22:23], vcc, s[22:23]
	v_max_f32_e32 v160, v160, v161
	v_mfma_f32_16x16x32_f16 v[118:121], v[58:61], v[38:41], v[114:117]
	v_cndmask_b32_e64 v159, v159, v160, s[22:23]
	v_add_u32_e32 v160, 19, v158
	v_cmp_le_i32_e32 vcc, v160, v149
	v_cmp_gt_i32_e64 s[24:25], v160, v162
	v_max_f32_e32 v160, v159, v159
	v_max_f32_e32 v161, v125, v125
	s_and_b64 s[26:27], vcc, s[24:25]
	v_max_f32_e32 v160, v160, v161
	v_cndmask_b32_e64 v159, v159, v160, s[26:27]
	v_add_u32_e32 v160, 32, v158
	v_cmp_le_i32_e32 vcc, v160, v149
	v_cmp_gt_i32_e64 s[24:25], v160, v162
	v_max_f32_e32 v160, v159, v159
	v_max_f32_e32 v161, v118, v118
	s_and_b64 s[24:25], vcc, s[24:25]
	v_max_f32_e32 v160, v160, v161
	v_cndmask_b32_e64 v159, v159, v160, s[24:25]
	v_add_u32_e32 v160, 33, v158
	v_cmp_le_i32_e32 vcc, v160, v149
	v_cmp_gt_i32_e64 s[28:29], v160, v162
	v_max_f32_e32 v160, v159, v159
	v_max_f32_e32 v161, v119, v119
	v_mfma_f32_16x16x32_f16 v[114:117], v[54:57], v[34:37], 0
	s_and_b64 s[28:29], vcc, s[28:29]
	v_max_f32_e32 v160, v160, v161
	v_cndmask_b32_e64 v159, v159, v160, s[28:29]
	v_add_u32_e32 v160, 34, v158
	v_cmp_le_i32_e32 vcc, v160, v149
	v_cmp_gt_i32_e64 s[30:31], v160, v162
	v_max_f32_e32 v160, v159, v159
	v_max_f32_e32 v161, v120, v120
	s_and_b64 s[30:31], vcc, s[30:31]
	v_max_f32_e32 v160, v160, v161
	v_mfma_f32_16x16x32_f16 v[114:117], v[50:53], v[38:41], v[114:117]
	v_cndmask_b32_e64 v159, v159, v160, s[30:31]
	v_add_u32_e32 v160, 35, v158
	v_cmp_le_i32_e32 vcc, v160, v149
	v_cmp_gt_i32_e64 s[34:35], v160, v162
	v_max_f32_e32 v160, v159, v159
	v_max_f32_e32 v161, v121, v121
	s_and_b64 s[36:37], vcc, s[34:35]
	v_max_f32_e32 v160, v160, v161
	v_cndmask_b32_e64 v159, v159, v160, s[36:37]
	v_add_u32_e32 v160, 48, v158
	v_cmp_le_i32_e32 vcc, v160, v149
	v_cmp_gt_i32_e64 s[34:35], v160, v162
	v_max_f32_e32 v160, v159, v159
	v_max_f32_e32 v161, v114, v114
	s_and_b64 s[34:35], vcc, s[34:35]
	v_max_f32_e32 v160, v160, v161
	v_cndmask_b32_e64 v159, v159, v160, s[34:35]
	v_add_u32_e32 v160, 49, v158
	v_cmp_le_i32_e32 vcc, v160, v149
	v_cmp_gt_i32_e64 s[38:39], v160, v162
	v_max_f32_e32 v160, v159, v159
	v_max_f32_e32 v161, v115, v115
	s_and_b64 s[38:39], vcc, s[38:39]
	v_max_f32_e32 v160, v160, v161
	v_cndmask_b32_e64 v159, v159, v160, s[38:39]
	v_add_u32_e32 v160, 50, v158
	v_cmp_le_i32_e32 vcc, v160, v149
	v_cmp_gt_i32_e64 s[40:41], v160, v162
	v_max_f32_e32 v160, v159, v159
	v_max_f32_e32 v161, v116, v116
	s_and_b64 s[40:41], vcc, s[40:41]
	v_max_f32_e32 v160, v160, v161
	v_cndmask_b32_e64 v159, v159, v160, s[40:41]
	v_add_u32_e32 v158, 51, v158
	v_cmp_le_i32_e32 vcc, v158, v149
	v_cmp_gt_i32_e64 s[42:43], v158, v162
	v_max_f32_e32 v158, v159, v159
	v_max_f32_e32 v160, v117, v117
	s_and_b64 s[42:43], vcc, s[42:43]
	v_max_f32_e32 v158, v158, v160
	v_cndmask_b32_e64 v158, v159, v158, s[42:43]
	v_add_f32_e32 v159, 0x41400000, v168
	v_cmp_gt_f32_e32 vcc, v158, v159
	s_cbranch_vccz .LBB0_949
	ds_bpermute_b32 v159, v173, v158
	v_max_f32_e32 v158, v158, v158
	s_waitcnt lgkmcnt(0)
	v_max_f32_e32 v159, v159, v159
	v_max_f32_e32 v158, v158, v159
	ds_bpermute_b32 v159, v222, v158
	s_waitcnt lgkmcnt(0)
	v_max3_f32 v159, v168, v158, v159
	v_sub_f32_e32 v158, v168, v159
	v_exp_f32_e32 v158, v158
	v_mov_b32_e32 v168, v159
	v_mul_f32_e32 v151, v151, v158
	v_pk_mul_f32 v[32:33], v[32:33], v[158:159] op_sel_hi:[1,0]
	v_pk_mul_f32 v[30:31], v[30:31], v[158:159] op_sel_hi:[1,0]
	v_pk_mul_f32 v[28:29], v[28:29], v[158:159] op_sel_hi:[1,0]
	v_pk_mul_f32 v[26:27], v[26:27], v[158:159] op_sel_hi:[1,0]
	v_pk_mul_f32 v[24:25], v[24:25], v[158:159] op_sel_hi:[1,0]
	v_pk_mul_f32 v[22:23], v[22:23], v[158:159] op_sel_hi:[1,0]
	v_pk_mul_f32 v[20:21], v[20:21], v[158:159] op_sel_hi:[1,0]
	v_pk_mul_f32 v[18:19], v[18:19], v[158:159] op_sel_hi:[1,0]
; #define MFMA16(a, b, c) __builtin_amdgcn_mfma_f32_16x16x32_f16((a), (b), (c), 0, 0, 0)
; __device__ __forceinline__ float shx(float v, int m) { return __shfl_xor(v, m); }
;     ...
;             f32x4 s[4];
; #pragma unroll
;             for (int t = 0; t < 4; ++t) { s[t] = MFMA16(ka[2 * t], qf[s_][0], z); s[t] = MFMA16(ka[2 * t + 1], qf[s_][1], s[t]); }
;             if (s_ == NS - 1) {
;                 const half_t* kpA = kf + (size_t)nbA * 2048; const half_t* kpB = kf + (size_t)nbB * 2048;
; #pragma unroll
;                 for (int i = 0; i < 4; ++i) { ka[i] = *(const half8*)(kpA + i * 512); ka[4 + i] = *(const half8*)(kpB + i * 512); }
;             }
;             if (MODE != 1) {
;                 float mx = -1e30f;
; #pragma unroll
;                 for (int t = 0; t < 4; ++t)
; #pragma unroll
;                     for (int r = 0; r < 4; ++r) { if (valid(s_, kbA + 16 * t + 4 * g + r)) mx = fmaxf(mx, s[t][r]); }
;                 if (__ballot(mx > m[s_] + RESC_THR) != 0ull) {
;                     mx = fmaxf(mx, shx(mx, 16)); mx = fmaxf(mx, shx(mx, 32));
;                     const float mn = fmaxf(m[s_], mx); const float corr = __builtin_amdgcn_exp2f(m[s_] - mn); m[s_] = mn; l[s_] = l[s_] * corr;
;                     if (PV) {
; #pragma unroll
;                         for (int dt = 0; dt < 4; ++dt) o[s_][dt] = o[s_][dt] * corr;
;                     }
;                 }
;             }
;             float p[4][4]; float ps = 0.f;
; #pragma unroll
;             for (int t = 0; t < 4; ++t)
; #pragma unroll
;                 for (int r = 0; r < 4; ++r) { p[t][r] = valid(s_, kbA + 16 * t + 4 * g + r) ? __builtin_amdgcn_exp2f(s[t][r] - m[s_]) : 0.f; if (MODE == 1) p[t][r] *= l[s_]; ps += p[t][r]; }
;             if (MODE != 1) l[s_] = l[s_] + ps;
;             if (PV) {
;                 const half8 pfA = {(half_t)p[0][0], (half_t)p[0][1], (half_t)p[0][2], (half_t)p[0][3], (half_t)p[1][0], (half_t)p[1][1], (half_t)p[1][2], (half_t)p[1][3]};
;                 const half8 pfB = {(half_t)p[2][0], (half_t)p[2][1], (half_t)p[2][2], (half_t)p[2][3], (half_t)p[3][0], (half_t)p[3][1], (half_t)p[3][2], (half_t)p[3][3]};
; #pragma unroll
;                 for (int dt = 0; dt < 4; ++dt) { o[s_][dt] = MFMA16(va[dt], pfA, o[s_][dt]); o[s_][dt] = MFMA16(va[4 + dt], pfB, o[s_][dt]); }
.LBB0_949:
	v_sub_f32_e32 v126, v126, v168
	v_sub_f32_e32 v122, v122, v168
	v_exp_f32_e32 v126, v126
	v_exp_f32_e32 v122, v122
	v_sub_f32_e32 v114, v114, v168
	v_exp_f32_e32 v114, v114
	v_sub_f32_e32 v118, v118, v168
	v_cndmask_b32_e64 v169, 0, v126, s[10:11]
	v_sub_f32_e32 v126, v127, v168
	v_cndmask_b32_e64 v183, 0, v122, s[16:17]
	v_sub_f32_e32 v122, v123, v168
	v_exp_f32_e32 v118, v118
	v_exp_f32_e32 v126, v126
	v_exp_f32_e32 v122, v122
	v_cndmask_b32_e64 v224, 0, v114, s[34:35]
	v_sub_f32_e32 v114, v115, v168
	v_exp_f32_e32 v114, v114
	v_cndmask_b32_e64 v187, 0, v118, s[24:25]
	v_sub_f32_e32 v118, v119, v168
	v_cndmask_b32_e64 v180, 0, v126, s[12:13]
	v_sub_f32_e32 v126, v128, v168
	v_cndmask_b32_e64 v184, 0, v122, s[20:21]
	v_sub_f32_e32 v122, v124, v168
	v_exp_f32_e32 v118, v118
	v_exp_f32_e32 v126, v126
	v_exp_f32_e32 v122, v122
	v_cndmask_b32_e64 v225, 0, v114, s[38:39]
	v_sub_f32_e32 v114, v116, v168
	v_exp_f32_e32 v114, v114
	v_cndmask_b32_e64 v188, 0, v118, s[28:29]
	v_sub_f32_e32 v118, v120, v168
	v_cndmask_b32_e64 v181, 0, v126, s[14:15]
	v_sub_f32_e32 v126, v129, v168
	v_cndmask_b32_e64 v185, 0, v122, s[22:23]
	v_sub_f32_e32 v122, v125, v168
	v_exp_f32_e32 v118, v118
	v_exp_f32_e32 v126, v126
	v_exp_f32_e32 v122, v122
	v_cndmask_b32_e64 v226, 0, v114, s[40:41]
	v_sub_f32_e32 v114, v117, v168
	v_exp_f32_e32 v114, v114
	s_add_i32 s50, s48, 1
	v_cndmask_b32_e64 v189, 0, v118, s[30:31]
	v_sub_f32_e32 v118, v121, v168
	s_cmp_lt_i32 s48, s46
	v_cndmask_b32_e64 v182, 0, v126, s[18:19]
	v_cndmask_b32_e64 v186, 0, v122, s[26:27]
	v_exp_f32_e32 v118, v118
	s_cselect_b32 s2, s50, s48
	v_cndmask_b32_e64 v227, 0, v114, s[42:43]
	v_cvt_pk_f16_f32 v117, v185, v186
	v_cvt_pk_f16_f32 v116, v183, v184
	v_cvt_pk_f16_f32 v115, v181, v182
	v_cvt_pk_f16_f32 v114, v169, v180
	s_lshl_b32 s2, s2, 6
	v_mfma_f32_16x16x32_f16 v[70:73], v[70:73], v[42:45], 0
	s_add_i32 s49, s2, s47
	s_ashr_i32 s2, s49, 5
	v_cndmask_b32_e64 v223, 0, v118, s[36:37]
	s_waitcnt vmcnt(0)
	v_mfma_f32_16x16x32_f16 v[30:33], v[106:109], v[114:117], v[30:33]
	s_min_i32 s44, s2, 0x1fe
	v_cvt_pk_f16_f32 v121, v226, v227
	v_cvt_pk_f16_f32 v120, v224, v225
	v_mfma_f32_16x16x32_f16 v[26:29], v[98:101], v[114:117], v[26:29]
	v_cvt_pk_f16_f32 v119, v189, v223
	v_cvt_pk_f16_f32 v118, v187, v188
	s_ashr_i32 s3, s2, 31
	v_mfma_f32_16x16x32_f16 v[22:25], v[90:93], v[114:117], v[22:25]
	s_ashr_i32 s45, s44, 31
	s_lshl_b64 s[2:3], s[2:3], 12
	s_lshl_b64 s[44:45], s[44:45], 12
	v_mfma_f32_16x16x32_f16 v[18:21], v[82:85], v[114:117], v[18:21]
	s_add_u32 s44, s44, 0x1000
	v_lshl_add_u64 v[158:159], v[154:155], 0, s[2:3]
	s_addc_u32 s45, s45, 0
	v_mfma_f32_16x16x32_f16 v[30:33], v[110:113], v[118:121], v[30:33]
	v_lshl_add_u64 v[160:161], v[154:155], 0, s[44:45]
	v_mfma_f32_16x16x32_f16 v[26:29], v[102:105], v[118:121], v[26:29]
	v_mfma_f32_16x16x32_f16 v[22:25], v[94:97], v[118:121], v[22:25]
	v_mfma_f32_16x16x32_f16 v[18:21], v[86:89], v[118:121], v[18:21]
	v_mfma_f32_16x16x32_f16 v[118:121], v[78:81], v[46:49], v[70:73]
	v_mfma_f32_16x16x32_f16 v[70:73], v[74:77], v[42:45], 0
	v_mfma_f32_16x16x32_f16 v[62:65], v[62:65], v[42:45], 0
	v_mfma_f32_16x16x32_f16 v[54:57], v[54:57], v[42:45], 0
	v_mfma_f32_16x16x32_f16 v[114:117], v[66:69], v[46:49], v[70:73]
	v_mfma_f32_16x16x32_f16 v[122:125], v[58:61], v[46:49], v[62:65]
	v_mfma_f32_16x16x32_f16 v[126:129], v[50:53], v[46:49], v[54:57]
	s_nop 2
	global_load_dwordx4 v[70:73], v[158:159], off
	global_load_dwordx4 v[62:65], v[160:161], off
	global_load_dwordx4 v[78:81], v[158:159], off offset:1024
	global_load_dwordx4 v[58:61], v[160:161], off offset:1024
	global_load_dwordx4 v[74:77], v[158:159], off offset:2048
	global_load_dwordx4 v[54:57], v[160:161], off offset:2048
	global_load_dwordx4 v[66:69], v[158:159], off offset:3072
	global_load_dwordx4 v[50:53], v[160:161], off offset:3072
	v_max_f32_e32 v158, v118, v118
	v_max_f32_e32 v158, 0xf149f2ca, v158
	v_cndmask_b32_e64 v158, v172, v158, s[10:11]
	v_max_f32_e32 v159, v119, v119
	v_max_f32_e32 v159, v158, v159
	v_cndmask_b32_e64 v158, v158, v159, s[12:13]
	v_max_f32_e32 v159, v120, v120
	v_max_f32_e32 v159, v158, v159
	v_cndmask_b32_e64 v158, v158, v159, s[14:15]
	v_max_f32_e32 v159, v121, v121
	v_max_f32_e32 v159, v158, v159
	v_cndmask_b32_e64 v158, v158, v159, s[18:19]
	v_max_f32_e32 v159, v114, v114
	v_max_f32_e32 v159, v158, v159
	v_cndmask_b32_e64 v158, v158, v159, s[16:17]
	v_max_f32_e32 v159, v158, v158
	v_max_f32_e32 v160, v115, v115
	v_max_f32_e32 v159, v159, v160
	v_cndmask_b32_e64 v158, v158, v159, s[20:21]
	v_max_f32_e32 v159, v158, v158
	v_max_f32_e32 v160, v116, v116
	v_max_f32_e32 v159, v159, v160
	v_cndmask_b32_e64 v158, v158, v159, s[22:23]
	v_max_f32_e32 v159, v158, v158
	v_max_f32_e32 v160, v117, v117
	v_max_f32_e32 v159, v159, v160
	v_cndmask_b32_e64 v158, v158, v159, s[26:27]
	v_max_f32_e32 v159, v158, v158
	v_max_f32_e32 v160, v122, v122
	v_max_f32_e32 v159, v159, v160
	v_cndmask_b32_e64 v158, v158, v159, s[24:25]
	v_max_f32_e32 v159, v158, v158
	v_max_f32_e32 v160, v123, v123
	v_max_f32_e32 v159, v159, v160
	v_cndmask_b32_e64 v158, v158, v159, s[28:29]
	v_max_f32_e32 v159, v158, v158
	v_max_f32_e32 v160, v124, v124
	v_max_f32_e32 v159, v159, v160
	v_cndmask_b32_e64 v158, v158, v159, s[30:31]
	v_max_f32_e32 v159, v158, v158
	v_max_f32_e32 v160, v125, v125
	v_max_f32_e32 v159, v159, v160
	v_cndmask_b32_e64 v158, v158, v159, s[36:37]
	v_max_f32_e32 v159, v158, v158
	v_max_f32_e32 v160, v126, v126
	v_max_f32_e32 v159, v159, v160
	v_cndmask_b32_e64 v158, v158, v159, s[34:35]
	v_max_f32_e32 v159, v158, v158
	v_max_f32_e32 v160, v127, v127
	v_max_f32_e32 v159, v159, v160
	v_cndmask_b32_e64 v158, v158, v159, s[38:39]
	v_max_f32_e32 v159, v158, v158
	v_max_f32_e32 v160, v128, v128
	v_max_f32_e32 v159, v159, v160
	v_cndmask_b32_e64 v158, v158, v159, s[40:41]
	v_max_f32_e32 v159, v158, v158
	v_max_f32_e32 v160, v129, v129
	v_max_f32_e32 v159, v159, v160
	v_cndmask_b32_e64 v158, v158, v159, s[42:43]
	v_add_f32_e32 v159, 0x41400000, v163
	v_cmp_gt_f32_e32 vcc, v158, v159
	s_cbranch_vccz .LBB0_951
	ds_bpermute_b32 v159, v173, v158
	v_max_f32_e32 v158, v158, v158
	s_waitcnt lgkmcnt(0)
	v_max_f32_e32 v159, v159, v159
	v_max_f32_e32 v158, v158, v159
	ds_bpermute_b32 v159, v222, v158
	s_waitcnt lgkmcnt(0)
	v_max3_f32 v159, v163, v158, v159
	v_sub_f32_e32 v158, v163, v159
	v_exp_f32_e32 v158, v158
	v_mov_b32_e32 v163, v159
	v_mul_f32_e32 v147, v147, v158
	v_pk_mul_f32 v[16:17], v[16:17], v[158:159] op_sel_hi:[1,0]
	v_pk_mul_f32 v[14:15], v[14:15], v[158:159] op_sel_hi:[1,0]
	v_pk_mul_f32 v[12:13], v[12:13], v[158:159] op_sel_hi:[1,0]
	v_pk_mul_f32 v[10:11], v[10:11], v[158:159] op_sel_hi:[1,0]
	v_pk_mul_f32 v[8:9], v[8:9], v[158:159] op_sel_hi:[1,0]
	v_pk_mul_f32 v[6:7], v[6:7], v[158:159] op_sel_hi:[1,0]
	v_pk_mul_f32 v[4:5], v[4:5], v[158:159] op_sel_hi:[1,0]
	v_pk_mul_f32 v[2:3], v[2:3], v[158:159] op_sel_hi:[1,0]

; __device__ __forceinline__ void c_unit(const ACtx& X, int b, int kvh, int qb, int lane) {
;     const int c = lane & 15, g = lane >> 4;
;     const int t0 = qb * 16, tq = t0 + c;
;     const size_t rowb = (size_t)b * S;
;     const half_t* P = X.proj;
;     half8 qf[3][2]; float m[3], l[3]; f32x4 o[3][4];
; #pragma unroll
;     for (int s_ = 0; s_ < 3; ++s_) { const half_t* qrow = P + (rowb + tq) * NPROJ + (28 + 3 * kvh + s_) * 64; qf[s_][0] = *(const half8*)(qrow + 8 * g); qf[s_][1] = *(const half8*)(qrow + 32 + 8 * g);
;         m[s_] = X.sinks[3 * kvh + s_] * LOG2E; l[s_] = (g == 0) ? 1.f : 0.f;
; #pragma unroll
;         for (int dt = 0; dt < 4; ++dt) o[s_][dt] = (f32x4){0.f, 0.f, 0.f, 0.f}; }
;     const int loff = (c * 4 + g) * 8;
;     const half_t* kb_ = X.kf + (size_t)((8 + kvh) * 2 + b) * 64 * S + loff;
;     const half_t* vb_ = X.vt + (size_t)((8 + kvh) * 2 + b) * 64 * S + loff;
;     auto valid = [&](int, int key) { return key <= tq && tq - key <= 127; };
;     const int lo_ = t0 - 127; const int kb0 = (lo_ > 0 ? lo_ : 0) & ~31;
;     auto kbw = [&](int it) { return kb0 + 64 * it; };
;     attn_runN<3, 0>(((((t0 + 15) >> 5) - (kb0 >> 5)) >> 1) + 1, kbw, S / 32 - 1, qf, kb_, vb_, valid, o, m, l, g);
.LBB0_1005:
	s_cmpk_gt_i32 s50, 0x17ff
	s_mov_b64 s[2:3], -1
	s_cbranch_scc0 .LBB0_1019
	s_add_i32 s2, s50, 0xffffe800
	s_lshr_b32 s84, s2, 11
	s_and_b32 s2, s50, 0x3ff
	s_lshl_b32 s2, s2, 4
	v_or_b32_e32 v183, s2, v165
	s_lshl_b64 s[6:7], s[84:85], 14
	v_sub_u32_e64 v0, s2, v206 clamp
	v_or_b32_e32 v184, s6, v183
	v_readfirstlane_b32 s6, v0
	v_mov_b32_e32 v185, s7
	s_bfe_u32 s7, s50, 0x90001
	s_lshr_b32 s2, s6, 5
	s_sub_i32 s7, s7, s2
	s_bfe_u32 s3, s50, 0x1000a
	s_ashr_i32 s43, s7, 1
	s_mul_i32 s42, s3, 0xc0
	s_waitcnt vmcnt(0)
	v_mov_b32_e32 v51, 0
	s_cmp_lt_i32 s43, 0
	v_mov_b32_e32 v50, 0
	v_mov_b32_e32 v49, 0
	v_mov_b32_e32 v48, 0
	v_mov_b32_e32 v47, 0
	v_mov_b32_e32 v46, 0
	v_mov_b32_e32 v45, 0
	v_mov_b32_e32 v44, 0
	v_mov_b32_e32 v43, 0
	v_mov_b32_e32 v42, 0
	v_mov_b32_e32 v41, 0
	v_mov_b32_e32 v40, 0
	v_mov_b32_e32 v39, 0
	v_mov_b32_e32 v38, 0
	v_mov_b32_e32 v37, 0
	v_mov_b32_e32 v36, 0
	v_mov_b32_e32 v35, 0
	v_mov_b32_e32 v34, 0
	v_mov_b32_e32 v33, 0
	v_mov_b32_e32 v32, 0
	v_mov_b32_e32 v31, 0
	v_mov_b32_e32 v30, 0
	v_mov_b32_e32 v29, 0
	v_mov_b32_e32 v28, 0
	v_mov_b32_e32 v27, 0
	v_mov_b32_e32 v26, 0
	v_mov_b32_e32 v25, 0
	v_mov_b32_e32 v24, 0
	v_mov_b32_e32 v23, 0
	v_mov_b32_e32 v22, 0
	v_mov_b32_e32 v21, 0
	v_mov_b32_e32 v20, 0
	v_mov_b32_e32 v19, 0
	v_mov_b32_e32 v18, 0
	v_mov_b32_e32 v17, 0
	v_mov_b32_e32 v16, 0
	v_mov_b32_e32 v15, 0
	v_mov_b32_e32 v14, 0
	v_mov_b32_e32 v13, 0
	v_mov_b32_e32 v12, 0
	v_mov_b32_e32 v11, 0
	v_mov_b32_e32 v10, 0
	v_mov_b32_e32 v9, 0
	v_mov_b32_e32 v8, 0
	v_mov_b32_e32 v7, 0
	v_mov_b32_e32 v6, 0
	v_mov_b32_e32 v5, 0
	v_mov_b32_e32 v4, 0
	v_mov_b32_e32 v0, v163
	v_mov_b32_e32 v173, v163
	v_mov_b32_e32 v167, v163
	s_cbranch_scc1 .LBB0_1020
	v_readlane_b32 s8, v253, 39
	v_readlane_b32 s9, v253, 40
	v_lshlrev_b32_e32 v0, 1, v164
	s_lshl_b32 s7, s3, 1
	v_mov_b64_e32 v[2:3], s[8:9]
	v_mad_u64_u32 v[2:3], s[8:9], v184, s82, v[2:3]
	v_mad_u32_u24 v3, v185, s82, v3
	s_lshl_b32 s8, s42, 1
	s_mov_b32 s9, s85
	v_lshl_add_u64 v[2:3], v[2:3], 0, s[8:9]
	s_mul_i32 s3, s3, 12
	v_lshl_add_u64 v[2:3], v[2:3], 0, v[0:1]
	v_mov_b32_e32 v0, s3
	s_waitcnt vmcnt(0)
	flat_load_dwordx4 v[52:55], v[2:3] offset:3584
	flat_load_dwordx4 v[56:59], v[2:3] offset:3648
	flat_load_dwordx4 v[60:63], v[2:3] offset:3712
	flat_load_dwordx4 v[64:67], v[2:3] offset:3776
	flat_load_dwordx4 v[68:71], v[2:3] offset:3840
	flat_load_dwordx4 v[72:75], v[2:3] offset:3904
	s_add_i32 s7, s84, s7
	global_load_dwordx3 v[2:4], v0, s[40:41]
	s_add_i32 s84, s7, 16
	s_lshl_b64 s[8:9], s[84:85], 21
	s_lshl_b32 s2, s2, 12
	v_lshl_add_u64 v[186:187], v[168:169], 0, s[8:9]
	s_and_b32 s44, s6, 0x3fe0
	s_mov_b32 s6, 0x3fb8aa3b
	s_add_i32 s84, s2, 0x1000
	s_mov_b32 s3, s85
	v_lshl_add_u64 v[188:189], v[180:181], 0, s[8:9]
	v_mov_b32_e32 v0, v1
	v_lshl_add_u64 v[112:113], v[188:189], 0, s[84:85]
	v_lshl_add_u64 v[108:109], v[188:189], 0, s[2:3]
	v_add_u32_e32 v190, 0xffffff80, v183
	s_mov_b32 s45, 0
	v_mov_b32_e32 v167, v163
	v_mov_b32_e32 v173, v163
	s_mov_b32 s46, s44
	v_lshl_add_u64 v[88:89], v[186:187], 0, s[84:85]
	v_lshl_add_u64 v[104:105], v[186:187], 0, s[2:3]
	global_load_dwordx4 v[76:79], v[88:89], off offset:3072
	global_load_dwordx4 v[92:95], v[104:105], off offset:3072
	global_load_dwordx4 v[80:83], v[88:89], off offset:2048
	global_load_dwordx4 v[100:103], v[104:105], off offset:2048
	global_load_dwordx4 v[84:87], v[88:89], off offset:1024
	global_load_dwordx4 v[96:99], v[104:105], off offset:1024
	global_load_dwordx4 v[88:91], v[88:89], off
	global_load_dwordx4 v[104:107], v[104:105], off
	s_waitcnt vmcnt(8)
	v_pk_mul_f32 v[156:157], v[2:3], s[6:7] op_sel_hi:[1,0]
	v_mul_f32_e32 v158, 0x3fb8aa3b, v4
	v_mov_b32_e32 v2, v1
	v_mov_b32_e32 v3, v1
	v_mov_b64_e32 v[6:7], v[2:3]
	v_mov_b64_e32 v[10:11], v[2:3]
	v_mov_b64_e32 v[14:15], v[2:3]
	v_mov_b64_e32 v[18:19], v[2:3]
	v_mov_b64_e32 v[22:23], v[2:3]
	v_mov_b64_e32 v[26:27], v[2:3]
	v_mov_b64_e32 v[30:31], v[2:3]
	v_mov_b64_e32 v[34:35], v[2:3]
	v_mov_b64_e32 v[38:39], v[2:3]
	v_mov_b64_e32 v[42:43], v[2:3]
	v_mov_b64_e32 v[46:47], v[2:3]
	v_mov_b64_e32 v[50:51], v[2:3]
	v_mov_b64_e32 v[4:5], v[0:1]
	v_mov_b64_e32 v[8:9], v[0:1]
	v_mov_b64_e32 v[12:13], v[0:1]
	v_mov_b64_e32 v[16:17], v[0:1]
	v_mov_b64_e32 v[20:21], v[0:1]
	v_mov_b64_e32 v[24:25], v[0:1]
	v_mov_b64_e32 v[28:29], v[0:1]
	v_mov_b64_e32 v[32:33], v[0:1]
	v_mov_b64_e32 v[36:37], v[0:1]
	v_mov_b64_e32 v[40:41], v[0:1]
	v_mov_b64_e32 v[44:45], v[0:1]
	v_mov_b64_e32 v[48:49], v[0:1]
	v_mov_b32_e32 v0, v163
; #define MFMA16(a, b, c) __builtin_amdgcn_mfma_f32_16x16x32_f16((a), (b), (c), 0, 0, 0)
; __device__ __forceinline__ float shx(float v, int m) { return __shfl_xor(v, m); }
;     ...
;     for (int it = 0; it < nit; ++it) {
;         const int kbN = kbof((it + 1 < nit) ? it + 1 : it);
;         const int nbA = kbN >> 5, nbB = (nbA + 1 <= maxblk) ? nbA + 1 : maxblk;
;         const f32x4 z = {0.f, 0.f, 0.f, 0.f};
; #pragma unroll
;         for (int s_ = 0; s_ < NS; ++s_) {
;             f32x4 s[4];
; #pragma unroll
;             for (int t = 0; t < 4; ++t) { s[t] = MFMA16(ka[2 * t], qf[s_][0], z); s[t] = MFMA16(ka[2 * t + 1], qf[s_][1], s[t]); }
;             if (s_ == NS - 1) {
;                 const half_t* kpA = kf + (size_t)nbA * 2048; const half_t* kpB = kf + (size_t)nbB * 2048;
; #pragma unroll
;                 for (int i = 0; i < 4; ++i) { ka[i] = *(const half8*)(kpA + i * 512); ka[4 + i] = *(const half8*)(kpB + i * 512); }
;             }
;             if (MODE != 1) {
;                 float mx = -1e30f;
; #pragma unroll
;                 for (int t = 0; t < 4; ++t)
; #pragma unroll
;                     for (int r = 0; r < 4; ++r) { if (valid(s_, kbA + 16 * t + 4 * g + r)) mx = fmaxf(mx, s[t][r]); }
;                 if (__ballot(mx > m[s_] + RESC_THR) != 0ull) {
;                     mx = fmaxf(mx, shx(mx, 16)); mx = fmaxf(mx, shx(mx, 32));
;                     const float mn = fmaxf(m[s_], mx); const float corr = __builtin_amdgcn_exp2f(m[s_] - mn); m[s_] = mn; l[s_] = l[s_] * corr;
;                     if (PV) {
; #pragma unroll
;                         for (int dt = 0; dt < 4; ++dt) o[s_][dt] = o[s_][dt] * corr;
;                     }
;                 }
;             }
.LBB0_1008:
	global_load_dwordx4 v[132:135], v[108:109], off
	global_load_dwordx4 v[124:127], v[108:109], off offset:1024
	global_load_dwordx4 v[116:119], v[108:109], off offset:2048
	s_nop 0
	global_load_dwordx4 v[108:111], v[108:109], off offset:3072
	s_nop 0
	global_load_dwordx4 v[136:139], v[112:113], off
	global_load_dwordx4 v[128:131], v[112:113], off offset:1024
	global_load_dwordx4 v[120:123], v[112:113], off offset:2048
	s_nop 0
	global_load_dwordx4 v[112:115], v[112:113], off offset:3072
	s_waitcnt vmcnt(8) lgkmcnt(0)
	v_mfma_f32_16x16x32_f16 v[140:143], v[104:107], v[52:55], 0
	v_add_u32_e32 v2, s46, v166
	v_cmp_le_i32_e32 vcc, v2, v183
	v_cmp_gt_i32_e64 s[6:7], v2, v190
	v_mfma_f32_16x16x32_f16 v[148:151], v[96:99], v[56:59], v[140:143]
	s_and_b64 s[6:7], vcc, s[6:7]
	v_sub_u32_e32 v159, v2, v183
	s_movk_i32 s2, 0xff7f
	v_cmp_lt_i32_e32 vcc, v2, v183
	v_cmp_lt_i32_e64 s[8:9], s2, v159
	s_nop 2
	v_max_f32_e32 v3, v148, v148
	v_max_f32_e32 v3, 0xf149f2ca, v3
	v_cndmask_b32_e64 v3, v172, v3, s[6:7]
	v_max_f32_e32 v159, v149, v149
	v_mfma_f32_16x16x32_f16 v[140:143], v[100:103], v[52:55], 0
	s_and_b64 s[8:9], vcc, s[8:9]
	v_max_f32_e32 v159, v3, v159
	v_cndmask_b32_e64 v3, v3, v159, s[8:9]
	v_add_u32_e32 v159, 2, v2
	v_cmp_le_i32_e32 vcc, v159, v183
	v_cmp_gt_i32_e64 s[10:11], v159, v190
	v_max_f32_e32 v159, v150, v150
	s_and_b64 s[10:11], vcc, s[10:11]
	v_max_f32_e32 v159, v3, v159
	v_mfma_f32_16x16x32_f16 v[152:155], v[92:95], v[56:59], v[140:143]
	v_cndmask_b32_e64 v3, v3, v159, s[10:11]
	v_add_u32_e32 v159, 3, v2
	v_cmp_le_i32_e32 vcc, v159, v183
	v_cmp_gt_i32_e64 s[12:13], v159, v190
	v_max_f32_e32 v159, v151, v151
	s_and_b64 s[14:15], vcc, s[12:13]
	v_max_f32_e32 v159, v3, v159
	v_cndmask_b32_e64 v3, v3, v159, s[14:15]
	v_add_u32_e32 v159, 16, v2
	v_cmp_le_i32_e32 vcc, v159, v183
	v_cmp_gt_i32_e64 s[12:13], v159, v190
	v_max_f32_e32 v159, v152, v152
	s_and_b64 s[12:13], vcc, s[12:13]
	v_max_f32_e32 v159, v3, v159
	v_cndmask_b32_e64 v3, v3, v159, s[12:13]
	v_add_u32_e32 v159, 17, v2
	v_cmp_le_i32_e32 vcc, v159, v183
	v_cmp_gt_i32_e64 s[16:17], v159, v190
	v_max_f32_e32 v159, v3, v3
	v_max_f32_e32 v160, v153, v153
	v_mfma_f32_16x16x32_f16 v[140:143], v[88:91], v[52:55], 0
	s_and_b64 s[16:17], vcc, s[16:17]
	v_max_f32_e32 v159, v159, v160
	v_cndmask_b32_e64 v3, v3, v159, s[16:17]
	v_add_u32_e32 v159, 18, v2
	v_cmp_le_i32_e32 vcc, v159, v183
	v_cmp_gt_i32_e64 s[18:19], v159, v190
	v_max_f32_e32 v159, v3, v3
	v_max_f32_e32 v160, v154, v154
	s_and_b64 s[18:19], vcc, s[18:19]
	v_max_f32_e32 v159, v159, v160
	v_mfma_f32_16x16x32_f16 v[144:147], v[84:87], v[56:59], v[140:143]
	v_cndmask_b32_e64 v3, v3, v159, s[18:19]
	v_add_u32_e32 v159, 19, v2
	v_cmp_le_i32_e32 vcc, v159, v183
	v_cmp_gt_i32_e64 s[20:21], v159, v190
	v_max_f32_e32 v159, v3, v3
	v_max_f32_e32 v160, v155, v155
	s_and_b64 s[22:23], vcc, s[20:21]
	v_max_f32_e32 v159, v159, v160
	v_cndmask_b32_e64 v3, v3, v159, s[22:23]
	v_add_u32_e32 v159, 32, v2
	v_cmp_le_i32_e32 vcc, v159, v183
	v_cmp_gt_i32_e64 s[20:21], v159, v190
	v_max_f32_e32 v159, v3, v3
	v_max_f32_e32 v160, v144, v144
	s_and_b64 s[20:21], vcc, s[20:21]
	v_max_f32_e32 v159, v159, v160
	v_cndmask_b32_e64 v3, v3, v159, s[20:21]
	v_add_u32_e32 v159, 33, v2
	v_cmp_le_i32_e32 vcc, v159, v183
	v_cmp_gt_i32_e64 s[24:25], v159, v190
	v_max_f32_e32 v159, v3, v3
	v_max_f32_e32 v160, v145, v145
	v_mfma_f32_16x16x32_f16 v[140:143], v[80:83], v[52:55], 0
	s_and_b64 s[24:25], vcc, s[24:25]
	v_max_f32_e32 v159, v159, v160
	v_cndmask_b32_e64 v3, v3, v159, s[24:25]
	v_add_u32_e32 v159, 34, v2
	v_cmp_le_i32_e32 vcc, v159, v183
	v_cmp_gt_i32_e64 s[26:27], v159, v190
	v_max_f32_e32 v159, v3, v3
	v_max_f32_e32 v160, v146, v146
	s_and_b64 s[26:27], vcc, s[26:27]
	v_max_f32_e32 v159, v159, v160
	v_mfma_f32_16x16x32_f16 v[140:143], v[76:79], v[56:59], v[140:143]
	v_cndmask_b32_e64 v3, v3, v159, s[26:27]
	v_add_u32_e32 v159, 35, v2
	v_cmp_le_i32_e32 vcc, v159, v183
	v_cmp_gt_i32_e64 s[28:29], v159, v190
	v_max_f32_e32 v159, v3, v3
	v_max_f32_e32 v160, v147, v147
	s_and_b64 s[30:31], vcc, s[28:29]
	v_max_f32_e32 v159, v159, v160
	v_cndmask_b32_e64 v3, v3, v159, s[30:31]
	v_add_u32_e32 v159, 48, v2
	v_cmp_le_i32_e32 vcc, v159, v183
	v_cmp_gt_i32_e64 s[28:29], v159, v190
	v_max_f32_e32 v159, v3, v3
	v_max_f32_e32 v160, v140, v140
	s_and_b64 s[28:29], vcc, s[28:29]
	v_max_f32_e32 v159, v159, v160
	v_cndmask_b32_e64 v3, v3, v159, s[28:29]
	v_add_u32_e32 v159, 49, v2
	v_cmp_le_i32_e32 vcc, v159, v183
	v_cmp_gt_i32_e64 s[34:35], v159, v190
	v_max_f32_e32 v159, v3, v3
	v_max_f32_e32 v160, v141, v141
	s_and_b64 s[34:35], vcc, s[34:35]
	v_max_f32_e32 v159, v159, v160
	v_cndmask_b32_e64 v3, v3, v159, s[34:35]
	v_add_u32_e32 v159, 50, v2
	v_cmp_le_i32_e32 vcc, v159, v183
	v_cmp_gt_i32_e64 s[36:37], v159, v190
	v_max_f32_e32 v159, v3, v3
	v_max_f32_e32 v160, v142, v142
	s_and_b64 s[36:37], vcc, s[36:37]
	v_max_f32_e32 v159, v159, v160
	v_cndmask_b32_e64 v3, v3, v159, s[36:37]
	v_add_u32_e32 v2, 51, v2
	v_cmp_le_i32_e32 vcc, v2, v183
	v_cmp_gt_i32_e64 s[38:39], v2, v190
	v_max_f32_e32 v2, v3, v3
	v_max_f32_e32 v159, v143, v143
	s_and_b64 s[38:39], vcc, s[38:39]
	v_max_f32_e32 v2, v2, v159
	v_cndmask_b32_e64 v2, v3, v2, s[38:39]
	v_add_f32_e32 v3, 0x41400000, v156
	v_cmp_gt_f32_e32 vcc, v2, v3
	s_cbranch_vccz .LBB0_1010
	v_and_b32_e32 v159, 64, v204
	v_xor_b32_e32 v3, 16, v204
	v_add_u32_e32 v159, 64, v159
	v_cmp_lt_i32_e32 vcc, v3, v159
	v_xor_b32_e32 v160, 32, v204
	s_nop 0
	v_cndmask_b32_e32 v3, v204, v3, vcc
	v_lshlrev_b32_e32 v3, 2, v3
	ds_bpermute_b32 v3, v3, v2
	v_max_f32_e32 v2, v2, v2
	v_cmp_lt_i32_e32 vcc, v160, v159
	s_waitcnt lgkmcnt(0)
	v_max_f32_e32 v3, v3, v3
	v_max_f32_e32 v2, v2, v3
	v_cndmask_b32_e32 v3, v204, v160, vcc
	v_lshlrev_b32_e32 v3, 2, v3
	ds_bpermute_b32 v3, v3, v2
	v_mov_b32_e32 v162, v158
	v_mov_b32_e32 v160, v156
	v_mov_b32_e32 v161, v157
	s_waitcnt lgkmcnt(0)
	v_max3_f32 v3, v156, v2, v3
	v_sub_f32_e32 v2, v156, v3
	v_exp_f32_e32 v2, v2
	v_mov_b32_e32 v160, v3
	v_mov_b32_e32 v156, v3
	v_mul_f32_e32 v0, v0, v2
	v_pk_mul_f32 v[50:51], v[50:51], v[2:3] op_sel_hi:[1,0]
	v_pk_mul_f32 v[48:49], v[48:49], v[2:3] op_sel_hi:[1,0]
	v_pk_mul_f32 v[46:47], v[46:47], v[2:3] op_sel_hi:[1,0]
	v_pk_mul_f32 v[44:45], v[44:45], v[2:3] op_sel_hi:[1,0]
	v_pk_mul_f32 v[42:43], v[42:43], v[2:3] op_sel_hi:[1,0]
	v_pk_mul_f32 v[40:41], v[40:41], v[2:3] op_sel_hi:[1,0]
	v_pk_mul_f32 v[38:39], v[38:39], v[2:3] op_sel_hi:[1,0]
	v_pk_mul_f32 v[36:37], v[36:37], v[2:3] op_sel_hi:[1,0]
	s_branch .LBB0_1011

; #define MFMA16(a, b, c) __builtin_amdgcn_mfma_f32_16x16x32_f16((a), (b), (c), 0, 0, 0)
; __device__ __forceinline__ float shx(float v, int m) { return __shfl_xor(v, m); }
;     ...
;             f32x4 s[4];
; #pragma unroll
;             for (int t = 0; t < 4; ++t) { s[t] = MFMA16(ka[2 * t], qf[s_][0], z); s[t] = MFMA16(ka[2 * t + 1], qf[s_][1], s[t]); }
;             if (s_ == NS - 1) {
;                 const half_t* kpA = kf + (size_t)nbA * 2048; const half_t* kpB = kf + (size_t)nbB * 2048;
; #pragma unroll
;                 for (int i = 0; i < 4; ++i) { ka[i] = *(const half8*)(kpA + i * 512); ka[4 + i] = *(const half8*)(kpB + i * 512); }
;             }
;             if (MODE != 1) {
;                 float mx = -1e30f;
; #pragma unroll
;                 for (int t = 0; t < 4; ++t)
; #pragma unroll
;                     for (int r = 0; r < 4; ++r) { if (valid(s_, kbA + 16 * t + 4 * g + r)) mx = fmaxf(mx, s[t][r]); }
;                 if (__ballot(mx > m[s_] + RESC_THR) != 0ull) {
;                     mx = fmaxf(mx, shx(mx, 16)); mx = fmaxf(mx, shx(mx, 32));
;                     const float mn = fmaxf(m[s_], mx); const float corr = __builtin_amdgcn_exp2f(m[s_] - mn); m[s_] = mn; l[s_] = l[s_] * corr;
;                     if (PV) {
; #pragma unroll
;                         for (int dt = 0; dt < 4; ++dt) o[s_][dt] = o[s_][dt] * corr;
;                     }
;                 }
;             }
;             float p[4][4]; float ps = 0.f;
; #pragma unroll
;             for (int t = 0; t < 4; ++t)
; #pragma unroll
;                 for (int r = 0; r < 4; ++r) { p[t][r] = valid(s_, kbA + 16 * t + 4 * g + r) ? __builtin_amdgcn_exp2f(s[t][r] - m[s_]) : 0.f; if (MODE == 1) p[t][r] *= l[s_]; ps += p[t][r]; }
;             if (MODE != 1) l[s_] = l[s_] + ps;
;             if (PV) {
;                 const half8 pfA = {(half_t)p[0][0], (half_t)p[0][1], (half_t)p[0][2], (half_t)p[0][3], (half_t)p[1][0], (half_t)p[1][1], (half_t)p[1][2], (half_t)p[1][3]};
;                 const half8 pfB = {(half_t)p[2][0], (half_t)p[2][1], (half_t)p[2][2], (half_t)p[2][3], (half_t)p[3][0], (half_t)p[3][1], (half_t)p[3][2], (half_t)p[3][3]};
; #pragma unroll
;                 for (int dt = 0; dt < 4; ++dt) { o[s_][dt] = MFMA16(va[dt], pfA, o[s_][dt]); o[s_][dt] = MFMA16(va[4 + dt], pfB, o[s_][dt]); }
.LBB0_1011:
	v_sub_f32_e32 v2, v148, v156
	v_sub_f32_e32 v3, v149, v156
	v_exp_f32_e32 v2, v2
	v_exp_f32_e32 v3, v3
	v_sub_f32_e32 v148, v150, v156
	v_sub_f32_e32 v149, v151, v156
	v_cndmask_b32_e64 v191, 0, v2, s[6:7]
	v_cndmask_b32_e64 v192, 0, v3, s[8:9]
	v_sub_f32_e32 v2, v152, v156
	v_sub_f32_e32 v3, v153, v156
	v_exp_f32_e32 v2, v2
	v_exp_f32_e32 v3, v3
	v_exp_f32_e32 v148, v148
	v_exp_f32_e32 v149, v149
	v_cndmask_b32_e64 v195, 0, v2, s[12:13]
	v_cndmask_b32_e64 v196, 0, v3, s[16:17]
	v_sub_f32_e32 v2, v144, v156
	v_sub_f32_e32 v3, v145, v156
	v_exp_f32_e32 v2, v2
	v_exp_f32_e32 v3, v3
	v_cndmask_b32_e64 v193, 0, v148, s[10:11]
	v_cndmask_b32_e64 v194, 0, v149, s[14:15]
	v_sub_f32_e32 v148, v154, v156
	v_sub_f32_e32 v149, v155, v156
	v_exp_f32_e32 v148, v148
	v_exp_f32_e32 v149, v149
	v_cndmask_b32_e64 v209, 0, v2, s[20:21]
	v_cndmask_b32_e64 v210, 0, v3, s[24:25]
	v_sub_f32_e32 v2, v140, v156
	v_sub_f32_e32 v3, v141, v156
	v_sub_f32_e32 v140, v142, v156
	v_sub_f32_e32 v141, v143, v156
	v_exp_f32_e32 v140, v140
	v_exp_f32_e32 v141, v141
	v_cndmask_b32_e64 v197, 0, v148, s[18:19]
	v_cndmask_b32_e64 v208, 0, v149, s[22:23]
	v_cndmask_b32_e64 v215, 0, v140, s[36:37]
	v_cndmask_b32_e64 v216, 0, v141, s[38:39]
	v_cvt_pk_f16_f32 v143, v197, v208
	v_cvt_pk_f16_f32 v142, v195, v196
	v_cvt_pk_f16_f32 v141, v193, v194
	v_cvt_pk_f16_f32 v140, v191, v192
	v_exp_f32_e32 v2, v2
	v_exp_f32_e32 v3, v3
	s_waitcnt vmcnt(0)
	v_mfma_f32_16x16x32_f16 v[48:51], v[132:135], v[140:143], v[48:51]
	v_sub_f32_e32 v144, v146, v156
	v_cndmask_b32_e64 v213, 0, v2, s[28:29]
	v_cndmask_b32_e64 v214, 0, v3, s[34:35]
	v_mfma_f32_16x16x32_f16 v[44:47], v[124:127], v[140:143], v[44:47]
	v_sub_f32_e32 v145, v147, v156
	v_exp_f32_e32 v144, v144
	v_exp_f32_e32 v145, v145
	v_mfma_f32_16x16x32_f16 v[40:43], v[116:119], v[140:143], v[40:43]
	v_cvt_pk_f16_f32 v147, v215, v216
	v_cndmask_b32_e64 v211, 0, v144, s[26:27]
	v_cndmask_b32_e64 v212, 0, v145, s[30:31]
	v_mfma_f32_16x16x32_f16 v[36:39], v[108:111], v[140:143], v[36:39]
	v_cvt_pk_f16_f32 v146, v213, v214
	v_cvt_pk_f16_f32 v145, v211, v212
	v_cvt_pk_f16_f32 v144, v209, v210
	v_mfma_f32_16x16x32_f16 v[140:143], v[104:107], v[60:63], 0
	v_mfma_f32_16x16x32_f16 v[152:155], v[96:99], v[64:67], v[140:143]
	v_mfma_f32_16x16x32_f16 v[140:143], v[100:103], v[60:63], 0
	v_mfma_f32_16x16x32_f16 v[148:151], v[92:95], v[64:67], v[140:143]
	s_nop 5
	v_max_f32_e32 v2, v152, v152
	v_max_f32_e32 v2, 0xf149f2ca, v2
	v_cndmask_b32_e64 v2, v172, v2, s[6:7]
	v_max_f32_e32 v3, v153, v153
	v_max_f32_e32 v3, v2, v3
	v_cndmask_b32_e64 v2, v2, v3, s[8:9]
	v_max_f32_e32 v3, v154, v154
	v_max_f32_e32 v3, v2, v3
	v_cndmask_b32_e64 v2, v2, v3, s[10:11]
	v_max_f32_e32 v3, v155, v155
	v_max_f32_e32 v3, v2, v3
	v_cndmask_b32_e64 v2, v2, v3, s[14:15]
	v_max_f32_e32 v3, v148, v148
	v_max_f32_e32 v3, v2, v3
	v_cndmask_b32_e64 v2, v2, v3, s[12:13]
	v_max_f32_e32 v3, v2, v2
	v_max_f32_e32 v156, v149, v149
	v_mfma_f32_16x16x32_f16 v[140:143], v[88:91], v[60:63], 0
	v_max_f32_e32 v3, v3, v156
	v_cndmask_b32_e64 v2, v2, v3, s[16:17]
	v_max_f32_e32 v3, v2, v2
	v_max_f32_e32 v156, v150, v150
	v_max_f32_e32 v3, v3, v156
	v_mfma_f32_16x16x32_f16 v[48:51], v[136:139], v[144:147], v[48:51]
	v_cndmask_b32_e64 v2, v2, v3, s[18:19]
	v_max_f32_e32 v3, v2, v2
	v_max_f32_e32 v156, v151, v151
	v_mfma_f32_16x16x32_f16 v[44:47], v[128:131], v[144:147], v[44:47]
	v_max_f32_e32 v3, v3, v156
	v_cndmask_b32_e64 v2, v2, v3, s[22:23]
	v_max_f32_e32 v3, v2, v2
	v_mfma_f32_16x16x32_f16 v[40:43], v[120:123], v[144:147], v[40:43]
	v_mfma_f32_16x16x32_f16 v[36:39], v[112:115], v[144:147], v[36:39]
	v_mfma_f32_16x16x32_f16 v[144:147], v[84:87], v[64:67], v[140:143]
	v_mfma_f32_16x16x32_f16 v[140:143], v[80:83], v[60:63], 0
	v_mfma_f32_16x16x32_f16 v[140:143], v[76:79], v[64:67], v[140:143]
	s_nop 5
	v_max_f32_e32 v156, v144, v144
	v_max_f32_e32 v3, v3, v156
	v_cndmask_b32_e64 v2, v2, v3, s[20:21]
	v_max_f32_e32 v3, v2, v2
	v_max_f32_e32 v156, v145, v145
	v_max_f32_e32 v3, v3, v156
	v_cndmask_b32_e64 v2, v2, v3, s[24:25]
	v_max_f32_e32 v3, v2, v2
	v_max_f32_e32 v156, v146, v146
	v_max_f32_e32 v3, v3, v156
	v_cndmask_b32_e64 v2, v2, v3, s[26:27]
	v_max_f32_e32 v3, v2, v2
	v_max_f32_e32 v156, v147, v147
	v_max_f32_e32 v3, v3, v156
	v_cndmask_b32_e64 v2, v2, v3, s[30:31]
	v_max_f32_e32 v3, v2, v2
	v_max_f32_e32 v156, v140, v140
	v_max_f32_e32 v3, v3, v156
	v_cndmask_b32_e64 v2, v2, v3, s[28:29]
	v_max_f32_e32 v3, v2, v2
	v_max_f32_e32 v156, v141, v141
	v_max_f32_e32 v3, v3, v156
	v_cndmask_b32_e64 v2, v2, v3, s[34:35]
	v_max_f32_e32 v3, v2, v2
	v_max_f32_e32 v156, v142, v142
	v_max_f32_e32 v3, v3, v156
	v_cndmask_b32_e64 v2, v2, v3, s[36:37]
	v_max_f32_e32 v3, v2, v2
	v_max_f32_e32 v156, v143, v143
	v_max_f32_e32 v3, v3, v156
	v_cndmask_b32_e64 v2, v2, v3, s[38:39]
	v_add_f32_e32 v3, 0x41400000, v161
	v_cmp_gt_f32_e32 vcc, v2, v3
	s_cbranch_vccz .LBB0_1013
	v_and_b32_e32 v156, 64, v204
	v_xor_b32_e32 v3, 16, v204
	v_add_u32_e32 v156, 64, v156
	v_cmp_lt_i32_e32 vcc, v3, v156
	v_xor_b32_e32 v157, 32, v204
	v_mov_b32_e32 v158, v160
	v_cndmask_b32_e32 v3, v204, v3, vcc
	v_lshlrev_b32_e32 v3, 2, v3
	ds_bpermute_b32 v3, v3, v2
	v_max_f32_e32 v2, v2, v2
	v_cmp_lt_i32_e32 vcc, v157, v156
	v_mov_b32_e32 v159, v161
	v_mov_b32_e32 v160, v162
	s_waitcnt lgkmcnt(0)
	v_max_f32_e32 v3, v3, v3
	v_max_f32_e32 v2, v2, v3
	v_cndmask_b32_e32 v3, v204, v157, vcc
	v_lshlrev_b32_e32 v3, 2, v3
	ds_bpermute_b32 v3, v3, v2
	s_waitcnt lgkmcnt(0)
	v_max3_f32 v3, v161, v2, v3
	v_sub_f32_e32 v2, v161, v3
	v_exp_f32_e32 v2, v2
	v_mov_b32_e32 v159, v3
	v_mov_b32_e32 v161, v3
	v_mul_f32_e32 v173, v173, v2
	v_pk_mul_f32 v[34:35], v[34:35], v[2:3] op_sel_hi:[1,0]
	v_pk_mul_f32 v[32:33], v[32:33], v[2:3] op_sel_hi:[1,0]
	v_pk_mul_f32 v[30:31], v[30:31], v[2:3] op_sel_hi:[1,0]
	v_pk_mul_f32 v[28:29], v[28:29], v[2:3] op_sel_hi:[1,0]
	v_pk_mul_f32 v[26:27], v[26:27], v[2:3] op_sel_hi:[1,0]
	v_pk_mul_f32 v[24:25], v[24:25], v[2:3] op_sel_hi:[1,0]
	v_pk_mul_f32 v[22:23], v[22:23], v[2:3] op_sel_hi:[1,0]
	v_pk_mul_f32 v[20:21], v[20:21], v[2:3] op_sel_hi:[1,0]
	s_branch .LBB0_1014

; #define MFMA16(a, b, c) __builtin_amdgcn_mfma_f32_16x16x32_f16((a), (b), (c), 0, 0, 0)
; __device__ __forceinline__ float shx(float v, int m) { return __shfl_xor(v, m); }
;     ...
;             f32x4 s[4];
; #pragma unroll
;             for (int t = 0; t < 4; ++t) { s[t] = MFMA16(ka[2 * t], qf[s_][0], z); s[t] = MFMA16(ka[2 * t + 1], qf[s_][1], s[t]); }
;             if (s_ == NS - 1) {
;                 const half_t* kpA = kf + (size_t)nbA * 2048; const half_t* kpB = kf + (size_t)nbB * 2048;
; #pragma unroll
;                 for (int i = 0; i < 4; ++i) { ka[i] = *(const half8*)(kpA + i * 512); ka[4 + i] = *(const half8*)(kpB + i * 512); }
;             }
;             if (MODE != 1) {
;                 float mx = -1e30f;
; #pragma unroll
;                 for (int t = 0; t < 4; ++t)
; #pragma unroll
;                     for (int r = 0; r < 4; ++r) { if (valid(s_, kbA + 16 * t + 4 * g + r)) mx = fmaxf(mx, s[t][r]); }
;                 if (__ballot(mx > m[s_] + RESC_THR) != 0ull) {
;                     mx = fmaxf(mx, shx(mx, 16)); mx = fmaxf(mx, shx(mx, 32));
;                     const float mn = fmaxf(m[s_], mx); const float corr = __builtin_amdgcn_exp2f(m[s_] - mn); m[s_] = mn; l[s_] = l[s_] * corr;
;                     if (PV) {
; #pragma unroll
;                         for (int dt = 0; dt < 4; ++dt) o[s_][dt] = o[s_][dt] * corr;
;                     }
;                 }
;             }
;             float p[4][4]; float ps = 0.f;
; #pragma unroll
;             for (int t = 0; t < 4; ++t)
; #pragma unroll
;                 for (int r = 0; r < 4; ++r) { p[t][r] = valid(s_, kbA + 16 * t + 4 * g + r) ? __builtin_amdgcn_exp2f(s[t][r] - m[s_]) : 0.f; if (MODE == 1) p[t][r] *= l[s_]; ps += p[t][r]; }
;             if (MODE != 1) l[s_] = l[s_] + ps;
;             if (PV) {
;                 const half8 pfA = {(half_t)p[0][0], (half_t)p[0][1], (half_t)p[0][2], (half_t)p[0][3], (half_t)p[1][0], (half_t)p[1][1], (half_t)p[1][2], (half_t)p[1][3]};
;                 const half8 pfB = {(half_t)p[2][0], (half_t)p[2][1], (half_t)p[2][2], (half_t)p[2][3], (half_t)p[3][0], (half_t)p[3][1], (half_t)p[3][2], (half_t)p[3][3]};
; #pragma unroll
;                 for (int dt = 0; dt < 4; ++dt) { o[s_][dt] = MFMA16(va[dt], pfA, o[s_][dt]); o[s_][dt] = MFMA16(va[4 + dt], pfB, o[s_][dt]); }
.LBB0_1014:
	v_sub_f32_e32 v152, v152, v161
	v_sub_f32_e32 v148, v148, v161
	v_exp_f32_e32 v152, v152
	v_exp_f32_e32 v148, v148
	v_sub_f32_e32 v140, v140, v161
	v_exp_f32_e32 v140, v140
	v_sub_f32_e32 v144, v144, v161
	v_cndmask_b32_e64 v162, 0, v152, s[6:7]
	v_sub_f32_e32 v152, v153, v161
	v_cndmask_b32_e64 v220, 0, v148, s[12:13]
	v_sub_f32_e32 v148, v149, v161
	v_exp_f32_e32 v144, v144
	v_exp_f32_e32 v152, v152
	v_exp_f32_e32 v148, v148
	v_cndmask_b32_e64 v228, 0, v140, s[28:29]
	v_sub_f32_e32 v140, v141, v161
	v_exp_f32_e32 v140, v140
	v_cndmask_b32_e64 v224, 0, v144, s[20:21]
	v_sub_f32_e32 v144, v145, v161
	v_cndmask_b32_e64 v217, 0, v152, s[8:9]
	v_sub_f32_e32 v152, v154, v161
	v_cndmask_b32_e64 v221, 0, v148, s[16:17]
	v_sub_f32_e32 v148, v150, v161
	v_exp_f32_e32 v144, v144
	v_exp_f32_e32 v152, v152
	v_exp_f32_e32 v148, v148
	v_cndmask_b32_e64 v229, 0, v140, s[34:35]
	v_sub_f32_e32 v140, v142, v161
	v_exp_f32_e32 v140, v140
	v_cndmask_b32_e64 v225, 0, v144, s[24:25]
	v_sub_f32_e32 v144, v146, v161
	v_cndmask_b32_e64 v218, 0, v152, s[10:11]
	v_sub_f32_e32 v152, v155, v161
	v_cndmask_b32_e64 v222, 0, v148, s[18:19]
	v_sub_f32_e32 v148, v151, v161
	v_exp_f32_e32 v144, v144
	v_exp_f32_e32 v152, v152
	v_exp_f32_e32 v148, v148
	v_cndmask_b32_e64 v230, 0, v140, s[36:37]
	v_sub_f32_e32 v140, v143, v161
	s_add_i32 s47, s45, 1
	v_exp_f32_e32 v140, v140
	s_cmp_lt_i32 s45, s43
	v_mfma_f32_16x16x32_f16 v[104:107], v[104:107], v[68:71], 0
	s_cselect_b32 s2, s47, s45
	v_cndmask_b32_e64 v226, 0, v144, s[26:27]
	v_sub_f32_e32 v144, v147, v161
	s_lshl_b32 s2, s2, 6
	v_cndmask_b32_e64 v219, 0, v152, s[14:15]
	v_cndmask_b32_e64 v223, 0, v148, s[22:23]
	v_exp_f32_e32 v144, v144
	s_add_i32 s46, s2, s44
	v_cndmask_b32_e64 v161, 0, v140, s[38:39]
	v_cvt_pk_f16_f32 v143, v222, v223
	v_cvt_pk_f16_f32 v142, v220, v221
	v_cvt_pk_f16_f32 v141, v218, v219
	v_cvt_pk_f16_f32 v140, v162, v217
	s_lshr_b32 s84, s46, 5
	v_mfma_f32_16x16x32_f16 v[152:155], v[96:99], v[72:75], v[104:107]
	s_min_u32 s33, s84, 0x1fe
	s_lshl_b64 s[2:3], s[84:85], 12
	s_lshl_b32 s33, s33, 12
	v_mfma_f32_16x16x32_f16 v[32:35], v[132:135], v[140:143], v[32:35]
	v_cndmask_b32_e64 v227, 0, v144, s[30:31]
	v_lshl_add_u64 v[156:157], v[186:187], 0, s[2:3]
	s_add_i32 s84, s33, 0x1000
	v_mfma_f32_16x16x32_f16 v[28:31], v[124:127], v[140:143], v[28:31]
	v_cvt_pk_f16_f32 v147, v230, v161
	v_cvt_pk_f16_f32 v146, v228, v229
	v_cvt_pk_f16_f32 v145, v226, v227
	v_mfma_f32_16x16x32_f16 v[24:27], v[116:119], v[140:143], v[24:27]
	v_cvt_pk_f16_f32 v144, v224, v225
	v_lshl_add_u64 v[2:3], v[186:187], 0, s[84:85]
	v_mfma_f32_16x16x32_f16 v[20:23], v[108:111], v[140:143], v[20:23]
	v_mfma_f32_16x16x32_f16 v[96:99], v[100:103], v[68:71], 0
	v_mfma_f32_16x16x32_f16 v[88:91], v[88:91], v[68:71], 0
	v_mfma_f32_16x16x32_f16 v[80:83], v[80:83], v[68:71], 0
	v_mfma_f32_16x16x32_f16 v[32:35], v[136:139], v[144:147], v[32:35]
	v_mfma_f32_16x16x32_f16 v[28:31], v[128:131], v[144:147], v[28:31]
	v_mfma_f32_16x16x32_f16 v[24:27], v[120:123], v[144:147], v[24:27]
	v_mfma_f32_16x16x32_f16 v[20:23], v[112:115], v[144:147], v[20:23]
	v_mfma_f32_16x16x32_f16 v[140:143], v[92:95], v[72:75], v[96:99]
	v_mfma_f32_16x16x32_f16 v[144:147], v[84:87], v[72:75], v[88:91]
	v_mfma_f32_16x16x32_f16 v[148:151], v[76:79], v[72:75], v[80:83]
	global_load_dwordx4 v[104:107], v[156:157], off
	s_nop 0
	global_load_dwordx4 v[88:91], v[2:3], off
	global_load_dwordx4 v[96:99], v[156:157], off offset:1024
	global_load_dwordx4 v[84:87], v[2:3], off offset:1024
	global_load_dwordx4 v[100:103], v[156:157], off offset:2048
	global_load_dwordx4 v[80:83], v[2:3], off offset:2048
	global_load_dwordx4 v[92:95], v[156:157], off offset:3072
	global_load_dwordx4 v[76:79], v[2:3], off offset:3072
	v_max_f32_e32 v2, v152, v152
	v_max_f32_e32 v2, 0xf149f2ca, v2
	v_cndmask_b32_e64 v2, v172, v2, s[6:7]
	v_max_f32_e32 v3, v153, v153
	v_max_f32_e32 v3, v2, v3
	v_cndmask_b32_e64 v2, v2, v3, s[8:9]
	v_max_f32_e32 v3, v154, v154
	v_max_f32_e32 v3, v2, v3
	v_cndmask_b32_e64 v2, v2, v3, s[10:11]
	v_max_f32_e32 v3, v155, v155
	v_max_f32_e32 v3, v2, v3
	v_cndmask_b32_e64 v2, v2, v3, s[14:15]
	v_max_f32_e32 v3, v140, v140
	v_max_f32_e32 v3, v2, v3
	v_cndmask_b32_e64 v2, v2, v3, s[12:13]
	v_max_f32_e32 v3, v2, v2
	v_max_f32_e32 v156, v141, v141
	v_max_f32_e32 v3, v3, v156
	v_cndmask_b32_e64 v2, v2, v3, s[16:17]
	v_max_f32_e32 v3, v2, v2
	v_max_f32_e32 v156, v142, v142
	v_max_f32_e32 v3, v3, v156
	v_cndmask_b32_e64 v2, v2, v3, s[18:19]
	v_max_f32_e32 v3, v2, v2
	v_max_f32_e32 v156, v143, v143
	v_max_f32_e32 v3, v3, v156
	v_cndmask_b32_e64 v2, v2, v3, s[22:23]
	v_max_f32_e32 v3, v2, v2
	v_max_f32_e32 v156, v144, v144
	v_max_f32_e32 v3, v3, v156
	v_cndmask_b32_e64 v2, v2, v3, s[20:21]
	v_max_f32_e32 v3, v2, v2
	v_max_f32_e32 v156, v145, v145
	v_max_f32_e32 v3, v3, v156
	v_cndmask_b32_e64 v2, v2, v3, s[24:25]
	v_max_f32_e32 v3, v2, v2
	v_max_f32_e32 v156, v146, v146
	v_max_f32_e32 v3, v3, v156
	v_cndmask_b32_e64 v2, v2, v3, s[26:27]
	v_max_f32_e32 v3, v2, v2
	v_max_f32_e32 v156, v147, v147
	v_max_f32_e32 v3, v3, v156
	v_cndmask_b32_e64 v2, v2, v3, s[30:31]
	v_max_f32_e32 v3, v2, v2
	v_max_f32_e32 v156, v148, v148
	v_max_f32_e32 v3, v3, v156
	v_cndmask_b32_e64 v2, v2, v3, s[28:29]
	v_max_f32_e32 v3, v2, v2
	v_max_f32_e32 v156, v149, v149
	v_max_f32_e32 v3, v3, v156
	v_cndmask_b32_e64 v2, v2, v3, s[34:35]
	v_max_f32_e32 v3, v2, v2
	v_max_f32_e32 v156, v150, v150
	v_max_f32_e32 v3, v3, v156
	v_cndmask_b32_e64 v2, v2, v3, s[36:37]
	v_max_f32_e32 v3, v2, v2
	v_max_f32_e32 v156, v151, v151
	v_max_f32_e32 v3, v3, v156
	v_cndmask_b32_e64 v2, v2, v3, s[38:39]
	v_add_f32_e32 v3, 0x41400000, v160
	v_cmp_gt_f32_e32 vcc, v2, v3
	s_cbranch_vccz .LBB0_1016
	v_and_b32_e32 v156, 64, v204
	v_xor_b32_e32 v3, 16, v204
	v_add_u32_e32 v156, 64, v156
	v_cmp_lt_i32_e32 vcc, v3, v156
	v_xor_b32_e32 v157, 32, v204
	s_nop 0
	v_cndmask_b32_e32 v3, v204, v3, vcc
	v_lshlrev_b32_e32 v3, 2, v3
	ds_bpermute_b32 v3, v3, v2
	v_max_f32_e32 v2, v2, v2
	v_cmp_lt_i32_e32 vcc, v157, v156
	s_waitcnt lgkmcnt(0)
	v_max_f32_e32 v3, v3, v3
	v_max_f32_e32 v2, v2, v3
	v_cndmask_b32_e32 v3, v204, v157, vcc
	v_lshlrev_b32_e32 v3, 2, v3
	ds_bpermute_b32 v3, v3, v2
	v_mov_b32_e32 v156, v158
	v_mov_b32_e32 v157, v159
	v_mov_b32_e32 v158, v160
	s_waitcnt lgkmcnt(0)
	v_max3_f32 v3, v160, v2, v3
	v_sub_f32_e32 v2, v160, v3
	v_exp_f32_e32 v2, v2
	v_mov_b32_e32 v158, v3
	v_mov_b32_e32 v160, v3
	v_mul_f32_e32 v167, v167, v2
	v_pk_mul_f32 v[18:19], v[18:19], v[2:3] op_sel_hi:[1,0]
	v_pk_mul_f32 v[16:17], v[16:17], v[2:3] op_sel_hi:[1,0]
	v_pk_mul_f32 v[14:15], v[14:15], v[2:3] op_sel_hi:[1,0]
	v_pk_mul_f32 v[12:13], v[12:13], v[2:3] op_sel_hi:[1,0]
	v_pk_mul_f32 v[10:11], v[10:11], v[2:3] op_sel_hi:[1,0]
	v_pk_mul_f32 v[8:9], v[8:9], v[2:3] op_sel_hi:[1,0]
	v_pk_mul_f32 v[6:7], v[6:7], v[2:3] op_sel_hi:[1,0]
	v_pk_mul_f32 v[4:5], v[4:5], v[2:3] op_sel_hi:[1,0]
	s_branch .LBB0_1017

; __device__ __forceinline__ void b_unit(const ACtx& X, int b, int h6, int fb, int lane) {
;     const int c = lane & 15, g = lane >> 4;
;     const int sh = 2 * (h6 >> 1), dil = 1 << sh, n = S >> sh, bpc = n >> 5;
;     const int r = fb / bpc, i0 = (fb % bpc) * 32;
;     const size_t rowb = (size_t)b * S;
;     const half_t* P = X.proj;
;     half8 qf[2][2]; int iqs[2], tls[2];
; #pragma unroll
;     for (int s_ = 0; s_ < 2; ++s_) { iqs[s_] = i0 + 16 * s_ + c; tls[s_] = iqs[s_] * dil + r; const half_t* qrow = P + (rowb + tls[s_]) * NPROJ + (10 + h6) * 64; qf[s_][0] = *(const half8*)(qrow + 8 * g); qf[s_][1] = *(const half8*)(qrow + 32 + 8 * g); }
;     const int loff = (c * 4 + g) * 8;
;     const half_t* kb_ = X.kf + (size_t)((2 + h6) * 2 + b) * 64 * S + (size_t)r * n * 64 + loff;
;     const half_t* vb_ = X.vt + (size_t)((2 + h6) * 2 + b) * 64 * S + (size_t)r * n * 64 + loff;
;     auto valid = [&](int s_, int kf) { return kf <= iqs[s_] && iqs[s_] - kf <= 128; };
;     float m[2] = {-1e30f, -1e30f}, l[2] = {0.f, 0.f}; f32x4 o[2][4];
; #pragma unroll
;     for (int s_ = 0; s_ < 2; ++s_)
; #pragma unroll
;         for (int dt = 0; dt < 4; ++dt) o[s_][dt] = (f32x4){0.f, 0.f, 0.f, 0.f};
;     const int lo_ = i0 - 128; const int kb0 = (lo_ > 0 ? lo_ : 0) & ~31;
;     auto kbw = [&](int it) { return kb0 + 64 * it; };
;     attn_runN<2, 0>(((((i0 + 31) >> 5) - (kb0 >> 5)) >> 1) + 1, kbw, (n >> 5) - 1, qf, kb_, vb_, valid, o, m, l, g);
.LBB0_1021:
	s_mul_hi_i32 s2, s50, 0x2aaaaaab
	s_lshr_b32 s3, s2, 31
	s_ashr_i32 s2, s2, 9
	s_add_i32 s6, s2, s3
	s_mul_i32 s2, s6, 0xc00
	s_sub_i32 s2, s50, s2
	s_ashr_i32 s42, s2, 9
	s_and_b32 s9, s42, -2
	s_lshr_b32 s43, 0x200, s9
	s_and_b32 s2, s2, 0x1ff
	s_sub_i32 s3, 9, s9
	s_add_i32 s43, s43, -1
	s_lshr_b32 s8, s2, s3
	s_and_b32 s2, s43, s2
	s_lshl_b32 s3, s2, 5
	v_or_b32_e32 v144, s3, v165
	v_or_b32_e32 v145, 16, v144
	v_lshlrev_b32_e32 v2, s9, v145
	v_add_u32_e32 v130, s8, v2
	v_sub_u32_e64 v2, s3, v205 clamp
	s_ashr_i32 s7, s6, 31
	v_readfirstlane_b32 s3, v2
	s_lshl_b64 s[44:45], s[6:7], 14
	s_lshr_b32 s7, s3, 5
	s_sub_i32 s2, s2, s7
	s_lshl_b32 s46, s42, 6
	v_lshlrev_b32_e32 v0, s9, v144
	s_ashr_i32 s53, s2, 1
	v_add_u32_e32 v0, s8, v0
	v_readfirstlane_b32 s52, v2
	s_cmp_gt_i32 s53, -1
	s_mov_b64 s[2:3], -1
	s_cbranch_scc0 .LBB0_1032
	s_lshl_b32 s2, s42, 1
	s_add_i32 s2, s6, s2
	s_add_i32 s2, s2, 4
	s_ashr_i32 s3, s2, 31
	s_lshr_b32 s9, 0x4000, s9
	s_lshl_b64 s[2:3], s[2:3], 21
	v_readlane_b32 s10, v253, 43
	s_mul_i32 s9, s9, s8
	v_readlane_b32 s11, v253, 44
	s_add_u32 s6, s10, s2
	s_addc_u32 s10, s11, s3
	s_lshl_b32 s11, s9, 7
	s_add_u32 s8, s6, s11
	s_addc_u32 s9, s10, 0
	v_readlane_b32 s12, v253, 41
	v_readlane_b32 s13, v253, 42
	s_add_u32 s2, s12, s2
	s_addc_u32 s3, s13, s3
	s_add_u32 s2, s2, s11
	s_addc_u32 s3, s3, 0
	v_mov_b32_e32 v183, v1
	s_ashr_i32 s47, s46, 31
	v_lshl_add_u64 v[138:139], s[2:3], 0, v[182:183]
	v_lshl_add_u64 v[140:141], s[8:9], 0, v[182:183]
	s_lshl_b64 s[2:3], s[46:47], 1
	v_readlane_b32 s8, v253, 39
	v_readlane_b32 s9, v253, 40
	s_add_u32 s2, s8, s2
	s_addc_u32 s3, s9, s3
	v_lshl_add_u64 v[132:133], s[44:45], 0, v[0:1]
	v_mov_b64_e32 v[2:3], s[2:3]
	v_mad_u64_u32 v[4:5], s[2:3], v132, s82, v[2:3]
	v_mad_i32_i24 v5, v133, s82, v5
	v_lshlrev_b32_e32 v6, 1, v164
	v_mov_b32_e32 v7, v1
	v_lshl_add_u64 v[4:5], v[4:5], 0, v[6:7]
	v_mov_b32_e32 v131, v1
	s_waitcnt vmcnt(0)
	flat_load_dwordx4 v[34:37], v[4:5] offset:1280
	flat_load_dwordx4 v[38:41], v[4:5] offset:1344
	v_lshl_add_u64 v[4:5], s[44:45], 0, v[130:131]
	v_mad_u64_u32 v[2:3], s[2:3], v4, s82, v[2:3]
	s_add_i32 s7, s7, 1
	s_min_i32 s2, s7, s43
	v_mad_i32_i24 v3, v5, s82, v3
	s_ashr_i32 s3, s2, 31
	v_lshl_add_u64 v[2:3], v[2:3], 0, v[6:7]
	s_lshl_b64 s[2:3], s[2:3], 12
	s_lshl_b32 s84, s52, 7
	flat_load_dwordx4 v[42:45], v[2:3] offset:1280
	flat_load_dwordx4 v[46:49], v[2:3] offset:1344
	v_lshl_add_u64 v[2:3], v[138:139], 0, s[2:3]
	v_lshl_add_u64 v[4:5], v[138:139], 0, s[84:85]
	flat_load_dwordx4 v[50:53], v[2:3] offset:3072
	flat_load_dwordx4 v[58:61], v[4:5] offset:3072
	flat_load_dwordx4 v[54:57], v[2:3] offset:2048
	flat_load_dwordx4 v[70:73], v[4:5] offset:2048
	flat_load_dwordx4 v[62:65], v[2:3] offset:1024
	flat_load_dwordx4 v[74:77], v[4:5] offset:1024
	flat_load_dwordx4 v[66:69], v[2:3]
	flat_load_dwordx4 v[78:81], v[4:5]
	v_mov_b32_e32 v4, v1
	v_mov_b32_e32 v5, v1
	v_mov_b32_e32 v173, v172
	v_mov_b32_e32 v2, v1
	v_mov_b32_e32 v3, v1
	v_mov_b64_e32 v[8:9], v[4:5]
	v_mov_b64_e32 v[12:13], v[4:5]
	v_mov_b64_e32 v[16:17], v[4:5]
	v_mov_b64_e32 v[20:21], v[4:5]
	v_mov_b64_e32 v[24:25], v[4:5]
	v_mov_b64_e32 v[28:29], v[4:5]
	v_mov_b64_e32 v[32:33], v[4:5]
	v_lshl_add_u64 v[82:83], v[140:141], 0, s[2:3]
	v_lshl_add_u64 v[84:85], v[140:141], 0, s[84:85]
	v_add_u32_e32 v131, 0xffffff7f, v144
	v_add_u32_e32 v146, 0xffffff8f, v144
	v_mov_b32_e32 v134, v1
	v_mov_b32_e32 v135, v1
	s_mov_b32 s54, 0
	v_mov_b64_e32 v[6:7], v[2:3]
	v_mov_b64_e32 v[10:11], v[2:3]
	v_mov_b64_e32 v[14:15], v[2:3]
	v_mov_b64_e32 v[18:19], v[2:3]
	v_mov_b64_e32 v[22:23], v[2:3]
	v_mov_b64_e32 v[26:27], v[2:3]
	v_mov_b64_e32 v[30:31], v[2:3]
	v_mov_b64_e32 v[136:137], v[172:173]
	s_mov_b32 s55, s52
